# band attention wave task rewritten by hand (gen_attn.py): specialised band/context pieces, scalar-base addressing, K prefetched one piece ahead
# speedup vs baseline: 1.0150x; 1.0088x over previous
.LBB0_459:
	v_mov_b32_e32 v37, v189
	s_mov_b32 s0, s33
	s_lshl_b32 s1, s0, 8
	s_and_b32 s1, s1, 0x700
	s_add_i32 s1, s1, s0
	s_and_b32 s4, s1, -8
	s_lshl_b32 s0, s89, 11
	s_add_i32 s2, s4, s0
	s_ashr_i32 s1, s2, 13
	s_lshl_b32 s3, s1, 8
	s_add_i32 s3, s3, 0x8000
	v_ashrrev_i32_e32 v46, 3, v37
	v_add_u32_e32 v4, s3, v46
	v_add_u32_e32 v22, 0x200, v37
	v_ashrrev_i32_e32 v5, 31, v4
	v_ashrrev_i32_e32 v48, 3, v22
	s_bfe_u32 s0, s2, 0x40009
	v_lshlrev_b64 v[4:5], 13, v[4:5]
	v_add_u32_e32 v6, s3, v48
	v_add_u32_e32 v28, 0x400, v37
	v_lshlrev_b32_e32 v20, 4, v37
	v_lshl_add_u64 v[4:5], s[60:61], 0, v[4:5]
	s_lshl_b32 s36, s0, 7
	v_ashrrev_i32_e32 v7, 31, v6
	v_ashrrev_i32_e32 v49, 3, v28
	v_and_b32_e32 v124, 0x70, v20
	v_lshl_add_u64 v[4:5], v[4:5], 0, s[36:37]
	v_lshlrev_b64 v[6:7], 13, v[6:7]
	v_add_u32_e32 v12, s3, v49
	v_add_u32_e32 v34, 0x600, v37
	v_lshl_add_u64 v[4:5], v[4:5], 0, v[124:125]
	v_lshl_add_u64 v[6:7], s[60:61], 0, v[6:7]
	v_ashrrev_i32_e32 v13, 31, v12
	v_ashrrev_i32_e32 v50, 3, v34
	v_add_co_u32_e32 v4, vcc, s66, v4
	v_lshl_add_u64 v[6:7], v[6:7], 0, s[36:37]
	v_lshlrev_b64 v[12:13], 13, v[12:13]
	v_add_u32_e32 v14, s3, v50
	v_addc_co_u32_e32 v5, vcc, 0, v5, vcc
	v_lshl_add_u64 v[6:7], v[6:7], 0, v[124:125]
	v_lshl_add_u64 v[12:13], s[60:61], 0, v[12:13]
	v_ashrrev_i32_e32 v15, 31, v14
	v_add_co_u32_e32 v8, vcc, s66, v6
	v_lshl_add_u64 v[12:13], v[12:13], 0, s[36:37]
	v_lshlrev_b64 v[14:15], 13, v[14:15]
	v_addc_co_u32_e32 v9, vcc, 0, v7, vcc
	v_lshl_add_u64 v[12:13], v[12:13], 0, v[124:125]
	v_lshl_add_u64 v[14:15], s[60:61], 0, v[14:15]
	s_lshl_b32 s1, s1, 4
	v_add_co_u32_e32 v12, vcc, s66, v12
	v_lshl_add_u64 v[14:15], v[14:15], 0, s[36:37]
	s_or_b32 s0, s1, s0
	v_addc_co_u32_e32 v13, vcc, 0, v13, vcc
	v_lshl_add_u64 v[14:15], v[14:15], 0, v[124:125]
	s_ashr_i32 s1, s0, 31
	s_barrier
	global_load_dwordx4 v[4:7], v[4:5], off
	s_nop 0
	global_load_dwordx4 v[8:11], v[8:9], off
	v_add_co_u32_e32 v16, vcc, s66, v14
	s_lshl_b64 s[0:1], s[0:1], 15
	s_nop 0
	v_addc_co_u32_e32 v17, vcc, 0, v15, vcc
	s_add_u32 s0, s46, s0
	v_ashrrev_i32_e32 v38, 5, v37
	v_ashrrev_i32_e32 v40, 5, v22
	v_add_u32_e32 v36, 0, v124
	global_load_dwordx4 v[12:15], v[12:13], off
	s_nop 0
	global_load_dwordx4 v[16:19], v[16:17], off
	s_addc_u32 s1, s47, s1
	v_and_b32_e32 v124, 0x1f0, v20
	v_ashrrev_i32_e32 v39, 31, v38
	v_ashrrev_i32_e32 v41, 31, v40
	v_ashrrev_i32_e32 v42, 5, v28
	v_ashrrev_i32_e32 v44, 5, v34
	v_lshl_add_u64 v[32:33], s[0:1], 0, v[124:125]
	v_lshlrev_b64 v[20:21], 9, v[38:39]
	v_lshlrev_b64 v[22:23], 9, v[40:41]
	v_ashrrev_i32_e32 v43, 31, v42
	v_ashrrev_i32_e32 v45, 31, v44
	v_lshl_add_u64 v[20:21], v[32:33], 0, v[20:21]
	v_lshl_add_u64 v[24:25], v[32:33], 0, v[22:23]
	v_lshlrev_b64 v[28:29], 9, v[42:43]
	v_lshlrev_b64 v[34:35], 9, v[44:45]
	global_load_dwordx4 v[20:23], v[20:21], off
	s_nop 0
	global_load_dwordx4 v[24:27], v[24:25], off
	v_lshl_add_u64 v[28:29], v[32:33], 0, v[28:29]
	v_lshl_add_u64 v[32:33], v[32:33], 0, v[34:35]
	global_load_dwordx4 v[28:31], v[28:29], off
	v_mad_u64_u32 v[46:47], s[0:1], v46, s67, v[36:37]
	global_load_dwordx4 v[32:35], v[32:33], off
	v_mov_b32_e32 v129, v125
	v_mov_b32_e32 v141, v125
	v_mov_b32_e32 v139, v125
	v_mov_b32_e32 v39, v125
	s_add_i32 s4, s4, s88
	v_mov_b32_e32 v47, v125
	s_mov_b32 s36, 1
	s_mov_b32 s90, 0
	v_mov_b32_e32 v170, 0xf149f2ca
	v_mov_b32_e32 v171, 0xf149f2ca
	v_mov_b32_e32 v172, 0xf149f2ca
	v_mov_b32_e32 v198, 0xf149f2ca
	s_mov_b32 s91, 0
	v_mov_b32_e32 v152, v125
	v_mov_b32_e32 v153, v125
	v_mov_b32_e32 v154, v125
	v_mov_b32_e32 v155, v125
	s_waitcnt vmcnt(7)
	ds_write_b128 v46, v[4:7] offset:20480
	v_mad_u64_u32 v[4:5], s[0:1], v48, s67, v[36:37]
	s_waitcnt vmcnt(6)
	ds_write_b128 v4, v[8:11] offset:20480
	v_mad_u64_u32 v[4:5], s[0:1], v49, s67, v[36:37]
	s_waitcnt vmcnt(5)
	ds_write_b128 v4, v[12:15] offset:20480
	v_mad_u64_u32 v[4:5], s[0:1], v50, s67, v[36:37]
	s_waitcnt vmcnt(4)
	ds_write_b128 v4, v[16:19] offset:20480
	v_add_u32_e32 v4, 0, v124
	v_mad_u64_u32 v[6:7], s[0:1], v38, s86, v[4:5]
	v_ashrrev_i32_e32 v50, 6, v37
	s_waitcnt vmcnt(3)
	ds_write_b128 v6, v[20:23] offset:57344
	v_mad_u64_u32 v[6:7], s[0:1], v40, s86, v[4:5]
	s_waitcnt vmcnt(2)
	ds_write_b128 v6, v[24:27] offset:57344
	v_mad_u64_u32 v[6:7], s[0:1], v42, s86, v[4:5]
	v_mad_u64_u32 v[4:5], s[0:1], v44, s86, v[4:5]
	s_waitcnt vmcnt(1)
	ds_write_b128 v6, v[28:31] offset:57344
	s_waitcnt vmcnt(0)
	ds_write_b128 v4, v[32:35] offset:57344
	v_add_u32_e32 v4, s2, v50
	s_movk_i32 s0, 0xa00
	v_mul_lo_u32 v5, v50, s0
	v_ashrrev_i32_e32 v44, 13, v4
	v_add_u32_e32 v51, 0, v5
	v_mov_b32_e32 v5, v189
	v_ashrrev_i32_e32 v45, 31, v44
	v_lshlrev_b32_e32 v6, 4, v50
	s_waitcnt lgkmcnt(0)
	s_barrier
	v_and_b32_e32 v127, 15, v189
	v_bfe_u32 v128, v189, 4, 2
	v_lshrrev_b32_e32 v209, 6, v189
	v_mov_b32_e32 v213, 0
	s_add_u32 s8, s52, 0x3e5000c8
	s_addc_u32 s9, s53, 0
	v_readfirstlane_b32 s0, v209
	v_lshlrev_b32_e32 v130, 13, v127
	v_lshlrev_b32_e32 v210, 4, v128
	v_mov_b32_e32 v211, s8
	v_mov_b32_e32 v212, s9
	s_nop 0
	v_mov_b32_e32 v220, s8
	v_mov_b32_e32 v221, s9
	s_nop 0
	global_load_dwordx2 v[220:221], v[220:221], off
	v_add_u32_e32 v130, v130, v210
	v_lshlrev_b32_e32 v214, 14, v127
	v_add_u32_e32 v214, v214, v210
	v_add_u32_e32 v215, 0x40000, v214
	v_add_u32_e32 v216, 0x80000, v214
	v_add_u32_e32 v217, 0xc0000, v214
	v_mul_u32_u24_e32 v136, 144, v127
	v_add_u32_e32 v136, v136, v210
	v_add_u32_e32 v136, 0x5000, v136
	v_mul_u32_u24_e32 v138, 0x210, v127
	v_add_u32_e32 v138, v138, v210
	v_add_u32_e32 v138, 0xe000, v138
	s_mul_i32 s10, s0, 0xa00
	v_mul_u32_u24_e32 v188, 0x280, v128
	v_lshl_add_u32 v188, v127, 1, v188
	v_add_u32_e32 v188, s10, v188
	v_mul_u32_u24_e32 v191, 160, v127
	v_add_u32_e32 v191, v191, v210
	v_add_u32_e32 v191, s10, v191
	v_lshlrev_b32_e32 v208, 14, v128
	v_lshl_add_u32 v208, v127, 1, v208
	s_add_u32 s0, s0, s2
	s_and_b32 s1, s0, 3
	s_bfe_u32 s3, s0, 0x70002
	s_bfe_u32 s4, s0, 0x40009
	s_lshr_b32 s5, s0, 13
	s_sub_u32 s6, s3, 4
	s_max_i32 s6, s6, 0
	s_min_i32 s6, s6, 0x78
	s_lshl_b32 s7, s1, 4
	s_sub_u32 s7, s7, 8
	s_max_i32 s7, s7, 0
	s_min_i32 s7, s7, 32
	s_lshl_b32 s8, s5, 26
	s_lshl_b32 s9, s4, 7
	s_add_u32 s8, s8, s9
	s_add_u32 s16, s60, s8
	s_addc_u32 s17, s61, 0
	s_lshl_b32 s8, s3, 6
	s_lshl_b32 s9, s1, 4
	s_add_u32 s8, s8, s9
	s_lshl_b32 s9, s8, 13
	s_add_u32 s9, s9, 0x800
	s_add_u32 s14, s16, s9
	s_addc_u32 s15, s17, 0
	global_load_dwordx4 v[4:7], v130, s[14:15]
	global_load_dwordx4 v[8:11], v130, s[14:15] offset:64
	s_lshl_b32 s9, s5, 13
	s_add_u32 s8, s8, s9
	s_lshl_b32 s8, s8, 12
	s_lshl_b32 s9, s4, 7
	s_add_u32 s8, s8, s9
	s_add_u32 s8, s8, 0x34c00800
	s_add_u32 s20, s52, s8
	s_addc_u32 s21, s53, 0
	s_add_u32 s16, s16, 0x1000
	s_addc_u32 s17, s17, 0
	s_lshl_b32 s8, s5, 4
	s_add_u32 s8, s8, s4
	s_lshl_b32 s8, s8, 20
	s_add_u32 s8, s8, 0x2ea00000
	s_add_u32 s18, s52, s8
	s_addc_u32 s19, s53, 0
	s_add_u32 s8, s6, 0
	s_lshl_b32 s8, s8, 6
	s_add_u32 s8, s8, s7
	s_lshl_b32 s8, s8, 13
	s_add_u32 s22, s16, s8
	s_addc_u32 s23, s17, 0
	global_load_dwordx4 v[12:15], v130, s[22:23]
	global_load_dwordx4 v[16:19], v130, s[22:23] offset:64
	s_add_u32 s8, s6, 0
	s_lshl_b32 s8, s8, 6
	s_add_u32 s8, s8, s7
	s_add_u32 s8, s8, 16
	s_lshl_b32 s8, s8, 13
	s_add_u32 s22, s16, s8
	s_addc_u32 s23, s17, 0
	global_load_dwordx4 v[20:23], v130, s[22:23]
	global_load_dwordx4 v[24:27], v130, s[22:23] offset:64
	s_add_u32 s8, s6, 1
	s_lshl_b32 s8, s8, 6
	s_add_u32 s8, s8, s7
	s_lshl_b32 s8, s8, 13
	s_add_u32 s22, s16, s8
	s_addc_u32 s23, s17, 0
	global_load_dwordx4 v[28:31], v130, s[22:23]
	global_load_dwordx4 v[32:35], v130, s[22:23] offset:64
	s_add_u32 s8, s6, 1
	s_lshl_b32 s8, s8, 6
	s_add_u32 s8, s8, s7
	s_add_u32 s8, s8, 16
	s_lshl_b32 s8, s8, 13
	s_add_u32 s22, s16, s8
	s_addc_u32 s23, s17, 0
	global_load_dwordx4 v[36:39], v130, s[22:23]
	global_load_dwordx4 v[40:43], v130, s[22:23] offset:64
	s_waitcnt vmcnt(10)
	v_readfirstlane_b32 s12, v220
	v_readfirstlane_b32 s13, v221
	s_mul_i32 s8, s4, 15
	s_add_u32 s8, s8, s6
	s_sub_u32 s8, s8, s3
	s_add_u32 s8, s8, 7
	s_mul_i32 s8, s8, 124
	s_add_u32 s12, s12, s8
	s_addc_u32 s13, s13, 0
	v_lshlrev_b32_e32 v209, 2, v128
	v_sub_u32_e32 v209, v127, v209
	s_lshl_b32 s8, s1, 4
	s_sub_i32 s9, s7, s8
	s_add_i32 s9, s9, 15
	v_add_u32_e32 v210, s9, v209
	v_med3_i32 v210, v210, 0, 30
	v_lshlrev_b32_e32 v192, 2, v210
	v_lshlrev_b32_e32 v210, 2, v128
	v_add_u32_e32 v210, s8, v210
	v_add_u32_e32 v210, -8, v210
	v_med3_i32 v210, v210, 0, 48
	v_add_u32_e32 v211, s7, v127
	v_sub_u32_e32 v211, v211, v210
	v_mov_b32_e32 v212, 0xf149f2ca
	v_cmp_gt_u32_e32 vcc, 16, v211
	s_nop 1
	v_cndmask_b32_e32 v200, v212, v213, vcc
	v_lshlrev_b32_e32 v209, 2, v128
	v_sub_u32_e32 v209, v127, v209
	s_lshl_b32 s8, s1, 4
	s_sub_i32 s9, s7, s8
	s_add_i32 s9, s9, 14
	v_add_u32_e32 v210, s9, v209
	v_med3_i32 v210, v210, 0, 30
	v_lshlrev_b32_e32 v193, 2, v210
	v_lshlrev_b32_e32 v210, 2, v128
	v_add_u32_e32 v210, s8, v210
	v_add_u32_e32 v210, -7, v210
	v_med3_i32 v210, v210, 0, 48
	v_add_u32_e32 v211, s7, v127
	v_sub_u32_e32 v211, v211, v210
	v_mov_b32_e32 v212, 0xf149f2ca
	v_cmp_gt_u32_e32 vcc, 16, v211
	s_nop 1
	v_cndmask_b32_e32 v201, v212, v213, vcc
	v_lshlrev_b32_e32 v209, 2, v128
	v_sub_u32_e32 v209, v127, v209
	s_lshl_b32 s8, s1, 4
	s_sub_i32 s9, s7, s8
	s_add_i32 s9, s9, 13
	v_add_u32_e32 v210, s9, v209
	v_med3_i32 v210, v210, 0, 30
	v_lshlrev_b32_e32 v194, 2, v210
	v_lshlrev_b32_e32 v210, 2, v128
	v_add_u32_e32 v210, s8, v210
	v_add_u32_e32 v210, -6, v210
	v_med3_i32 v210, v210, 0, 48
	v_add_u32_e32 v211, s7, v127
	v_sub_u32_e32 v211, v211, v210
	v_mov_b32_e32 v212, 0xf149f2ca
	v_cmp_gt_u32_e32 vcc, 16, v211
	s_nop 1
	v_cndmask_b32_e32 v202, v212, v213, vcc
	v_lshlrev_b32_e32 v209, 2, v128
	v_sub_u32_e32 v209, v127, v209
	s_lshl_b32 s8, s1, 4
	s_sub_i32 s9, s7, s8
	s_add_i32 s9, s9, 12
	v_add_u32_e32 v210, s9, v209
	v_med3_i32 v210, v210, 0, 30
	v_lshlrev_b32_e32 v195, 2, v210
	v_lshlrev_b32_e32 v210, 2, v128
	v_add_u32_e32 v210, s8, v210
	v_add_u32_e32 v210, -5, v210
	v_med3_i32 v210, v210, 0, 48
	v_add_u32_e32 v211, s7, v127
	v_sub_u32_e32 v211, v211, v210
	v_mov_b32_e32 v212, 0xf149f2ca
	v_cmp_gt_u32_e32 vcc, 16, v211
	s_nop 1
	v_cndmask_b32_e32 v203, v212, v213, vcc
	v_lshlrev_b32_e32 v209, 2, v128
	v_sub_u32_e32 v209, v127, v209
	s_lshl_b32 s8, s1, 4
	s_sub_i32 s9, s7, s8
	s_add_i32 s9, s9, 31
	v_add_u32_e32 v210, s9, v209
	v_med3_i32 v210, v210, 0, 30
	v_lshlrev_b32_e32 v196, 2, v210
	v_lshlrev_b32_e32 v210, 2, v128
	v_add_u32_e32 v210, s8, v210
	v_add_u32_e32 v210, -8, v210
	v_med3_i32 v210, v210, 0, 48
	v_add_u32_e32 v211, s7, v127
	v_add_u32_e32 v211, 16, v211
	v_sub_u32_e32 v211, v211, v210
	v_mov_b32_e32 v212, 0xf149f2ca
	v_cmp_gt_u32_e32 vcc, 16, v211
	s_nop 1
	v_cndmask_b32_e32 v204, v212, v213, vcc
	v_lshlrev_b32_e32 v209, 2, v128
	v_sub_u32_e32 v209, v127, v209
	s_lshl_b32 s8, s1, 4
	s_sub_i32 s9, s7, s8
	s_add_i32 s9, s9, 30
	v_add_u32_e32 v210, s9, v209
	v_med3_i32 v210, v210, 0, 30
	v_lshlrev_b32_e32 v197, 2, v210
	v_lshlrev_b32_e32 v210, 2, v128
	v_add_u32_e32 v210, s8, v210
	v_add_u32_e32 v210, -7, v210
	v_med3_i32 v210, v210, 0, 48
	v_add_u32_e32 v211, s7, v127
	v_add_u32_e32 v211, 16, v211
	v_sub_u32_e32 v211, v211, v210
	v_mov_b32_e32 v212, 0xf149f2ca
	v_cmp_gt_u32_e32 vcc, 16, v211
	s_nop 1
	v_cndmask_b32_e32 v205, v212, v213, vcc
	v_lshlrev_b32_e32 v209, 2, v128
	v_sub_u32_e32 v209, v127, v209
	s_lshl_b32 s8, s1, 4
	s_sub_i32 s9, s7, s8
	s_add_i32 s9, s9, 29
	v_add_u32_e32 v210, s9, v209
	v_med3_i32 v210, v210, 0, 30
	v_lshlrev_b32_e32 v198, 2, v210
	v_lshlrev_b32_e32 v210, 2, v128
	v_add_u32_e32 v210, s8, v210
	v_add_u32_e32 v210, -6, v210
	v_med3_i32 v210, v210, 0, 48
	v_add_u32_e32 v211, s7, v127
	v_add_u32_e32 v211, 16, v211
	v_sub_u32_e32 v211, v211, v210
	v_mov_b32_e32 v212, 0xf149f2ca
	v_cmp_gt_u32_e32 vcc, 16, v211
	s_nop 1
	v_cndmask_b32_e32 v206, v212, v213, vcc
	v_lshlrev_b32_e32 v209, 2, v128
	v_sub_u32_e32 v209, v127, v209
	s_lshl_b32 s8, s1, 4
	s_sub_i32 s9, s7, s8
	s_add_i32 s9, s9, 28
	v_add_u32_e32 v210, s9, v209
	v_med3_i32 v210, v210, 0, 30
	v_lshlrev_b32_e32 v199, 2, v210
	v_lshlrev_b32_e32 v210, 2, v128
	v_add_u32_e32 v210, s8, v210
	v_add_u32_e32 v210, -5, v210
	v_med3_i32 v210, v210, 0, 48
	v_add_u32_e32 v211, s7, v127
	v_add_u32_e32 v211, 16, v211
	v_sub_u32_e32 v211, v211, v210
	v_mov_b32_e32 v212, 0xf149f2ca
	v_cmp_gt_u32_e32 vcc, 16, v211
	s_nop 1
	v_cndmask_b32_e32 v207, v212, v213, vcc
	v_mov_b32_e32 v172, 0xf149f2ca
	v_mov_b32_e32 v176, 0
	v_mov_b32_e32 v173, 0xf149f2ca
	v_mov_b32_e32 v177, 0
	v_mov_b32_e32 v174, 0xf149f2ca
	v_mov_b32_e32 v178, 0
	v_mov_b32_e32 v175, 0xf149f2ca
	v_mov_b32_e32 v179, 0
	v_mov_b32_e32 v100, 0
	v_mov_b32_e32 v101, 0
	v_mov_b32_e32 v102, 0
	v_mov_b32_e32 v103, 0
	v_mov_b32_e32 v132, 0
	v_mov_b32_e32 v133, 0
	v_mov_b32_e32 v134, 0
	v_mov_b32_e32 v135, 0
	v_mov_b32_e32 v140, 0
	v_mov_b32_e32 v141, 0
	v_mov_b32_e32 v142, 0
	v_mov_b32_e32 v143, 0
	v_mov_b32_e32 v144, 0
	v_mov_b32_e32 v145, 0
	v_mov_b32_e32 v146, 0
	v_mov_b32_e32 v147, 0
	s_add_u32 s26, s12, 0
	s_addc_u32 s27, s13, 0
	global_load_dword v148, v192, s[26:27]
	global_load_dword v149, v193, s[26:27]
	global_load_dword v150, v194, s[26:27]
	global_load_dword v151, v195, s[26:27]
	s_add_u32 s26, s12, 0
	s_addc_u32 s27, s13, 0
	global_load_dword v152, v196, s[26:27]
	global_load_dword v153, v197, s[26:27]
	global_load_dword v154, v198, s[26:27]
	global_load_dword v155, v199, s[26:27]
	s_add_u32 s26, s12, 124
	s_addc_u32 s27, s13, 0
	global_load_dword v156, v192, s[26:27]
	global_load_dword v157, v193, s[26:27]
	global_load_dword v158, v194, s[26:27]
	global_load_dword v159, v195, s[26:27]
	s_add_u32 s26, s12, 124
	s_addc_u32 s27, s13, 0
	global_load_dword v160, v196, s[26:27]
	global_load_dword v161, v197, s[26:27]
	global_load_dword v162, v198, s[26:27]
	global_load_dword v163, v199, s[26:27]
	s_add_u32 s8, s6, 0
	s_lshl_b32 s8, s8, 6
	s_add_u32 s8, s8, s7
	s_lshl_b32 s8, s8, 1
	s_add_u32 s24, s18, s8
	s_addc_u32 s25, s19, 0
	global_load_dwordx4 v[44:47], v214, s[24:25]
	global_load_dwordx4 v[48:51], v215, s[24:25]
	global_load_dwordx4 v[52:55], v216, s[24:25]
	global_load_dwordx4 v[56:59], v217, s[24:25]
	s_add_u32 s8, s6, 1
	s_lshl_b32 s8, s8, 6
	s_add_u32 s8, s8, s7
	s_lshl_b32 s8, s8, 1
	s_add_u32 s24, s18, s8
	s_addc_u32 s25, s19, 0
	global_load_dwordx4 v[60:63], v214, s[24:25]
	global_load_dwordx4 v[64:67], v215, s[24:25]
	global_load_dwordx4 v[68:71], v216, s[24:25]
	global_load_dwordx4 v[72:75], v217, s[24:25]
	s_waitcnt vmcnt(24)
	v_mov_b32_e32 v76, 0
	v_mov_b32_e32 v77, 0
	v_mov_b32_e32 v78, 0
	v_mov_b32_e32 v79, 0
	v_mov_b32_e32 v84, 0
	v_mov_b32_e32 v85, 0
	v_mov_b32_e32 v86, 0
	v_mov_b32_e32 v87, 0
	v_mov_b32_e32 v88, 0
	v_mov_b32_e32 v89, 0
	v_mov_b32_e32 v90, 0
	v_mov_b32_e32 v91, 0
	v_mov_b32_e32 v96, 0
	v_mov_b32_e32 v97, 0
	v_mov_b32_e32 v98, 0
	v_mov_b32_e32 v99, 0
	s_nop 1
	v_mfma_f32_16x16x32_bf16 v[76:79], v[4:7], v[12:15], v[76:79]
	v_mfma_f32_16x16x32_bf16 v[76:79], v[8:11], v[16:19], v[76:79]
	v_mfma_f32_16x16x32_bf16 v[84:87], v[4:7], v[20:23], v[84:87]
	v_mfma_f32_16x16x32_bf16 v[84:87], v[8:11], v[24:27], v[84:87]
	v_mfma_f32_16x16x32_bf16 v[88:91], v[4:7], v[28:31], v[88:91]
	v_mfma_f32_16x16x32_bf16 v[88:91], v[8:11], v[32:35], v[88:91]
	v_mfma_f32_16x16x32_bf16 v[96:99], v[4:7], v[36:39], v[96:99]
	v_mfma_f32_16x16x32_bf16 v[96:99], v[8:11], v[40:43], v[96:99]
	s_nop 3
	s_add_u32 s8, s6, 2
	s_lshl_b32 s8, s8, 6
	s_add_u32 s8, s8, s7
	s_lshl_b32 s8, s8, 13
	s_add_u32 s22, s16, s8
	s_addc_u32 s23, s17, 0
	global_load_dwordx4 v[12:15], v130, s[22:23]
	global_load_dwordx4 v[16:19], v130, s[22:23] offset:64
	s_add_u32 s8, s6, 2
	s_lshl_b32 s8, s8, 6
	s_add_u32 s8, s8, s7
	s_add_u32 s8, s8, 16
	s_lshl_b32 s8, s8, 13
	s_add_u32 s22, s16, s8
	s_addc_u32 s23, s17, 0
	global_load_dwordx4 v[20:23], v130, s[22:23]
	global_load_dwordx4 v[24:27], v130, s[22:23] offset:64
	s_add_u32 s8, s6, 3
	s_lshl_b32 s8, s8, 6
	s_add_u32 s8, s8, s7
	s_lshl_b32 s8, s8, 13
	s_add_u32 s22, s16, s8
	s_addc_u32 s23, s17, 0
	global_load_dwordx4 v[28:31], v130, s[22:23]
	global_load_dwordx4 v[32:35], v130, s[22:23] offset:64
	s_add_u32 s8, s6, 3
	s_lshl_b32 s8, s8, 6
	s_add_u32 s8, s8, s7
	s_add_u32 s8, s8, 16
	s_lshl_b32 s8, s8, 13
	s_add_u32 s22, s16, s8
	s_addc_u32 s23, s17, 0
	global_load_dwordx4 v[36:39], v130, s[22:23]
	global_load_dwordx4 v[40:43], v130, s[22:23] offset:64
	s_nop 7
	s_waitcnt vmcnt(16)
	v_mul_f32_e32 v76, 0x3e000000, v76
	v_add_f32_e32 v148, v148, v200
	v_add_f32_e32 v76, v76, v148
	v_mul_f32_e32 v77, 0x3e000000, v77
	v_add_f32_e32 v149, v149, v201
	v_add_f32_e32 v77, v77, v149
	v_mul_f32_e32 v78, 0x3e000000, v78
	v_add_f32_e32 v150, v150, v202
	v_add_f32_e32 v78, v78, v150
	v_mul_f32_e32 v79, 0x3e000000, v79
	v_add_f32_e32 v151, v151, v203
	v_add_f32_e32 v79, v79, v151
	v_mul_f32_e32 v84, 0x3e000000, v84
	v_add_f32_e32 v152, v152, v204
	v_add_f32_e32 v84, v84, v152
	v_mul_f32_e32 v85, 0x3e000000, v85
	v_add_f32_e32 v153, v153, v205
	v_add_f32_e32 v85, v85, v153
	v_mul_f32_e32 v86, 0x3e000000, v86
	v_add_f32_e32 v154, v154, v206
	v_add_f32_e32 v86, v86, v154
	v_mul_f32_e32 v87, 0x3e000000, v87
	v_add_f32_e32 v155, v155, v207
	v_add_f32_e32 v87, v87, v155
	v_mul_f32_e32 v88, 0x3e000000, v88
	v_add_f32_e32 v156, v156, v200
	v_add_f32_e32 v88, v88, v156
	v_mul_f32_e32 v89, 0x3e000000, v89
	v_add_f32_e32 v157, v157, v201
	v_add_f32_e32 v89, v89, v157
	v_mul_f32_e32 v90, 0x3e000000, v90
	v_add_f32_e32 v158, v158, v202
	v_add_f32_e32 v90, v90, v158
	v_mul_f32_e32 v91, 0x3e000000, v91
	v_add_f32_e32 v159, v159, v203
	v_add_f32_e32 v91, v91, v159
	v_mul_f32_e32 v96, 0x3e000000, v96
	v_add_f32_e32 v160, v160, v204
	v_add_f32_e32 v96, v96, v160
	v_mul_f32_e32 v97, 0x3e000000, v97
	v_add_f32_e32 v161, v161, v205
	v_add_f32_e32 v97, v97, v161
	v_mul_f32_e32 v98, 0x3e000000, v98
	v_add_f32_e32 v162, v162, v206
	v_add_f32_e32 v98, v98, v162
	v_mul_f32_e32 v99, 0x3e000000, v99
	v_add_f32_e32 v163, v163, v207
	v_add_f32_e32 v99, v99, v163
	v_max3_f32 v184, v76, v84, v88
	v_max_f32_e32 v184, v184, v96
	v_max3_f32 v185, v77, v85, v89
	v_max_f32_e32 v185, v185, v97
	v_max3_f32 v186, v78, v86, v90
	v_max_f32_e32 v186, v186, v98
	v_max3_f32 v187, v79, v87, v91
	v_max_f32_e32 v187, v187, v99
	s_nop 0
	v_max_f32_dpp v184, v184, v184 quad_perm:[1,0,3,2] row_mask:0xf bank_mask:0xf
	v_max_f32_dpp v185, v185, v185 quad_perm:[1,0,3,2] row_mask:0xf bank_mask:0xf
	v_max_f32_dpp v186, v186, v186 quad_perm:[1,0,3,2] row_mask:0xf bank_mask:0xf
	v_max_f32_dpp v187, v187, v187 quad_perm:[1,0,3,2] row_mask:0xf bank_mask:0xf
	v_max_f32_dpp v184, v184, v184 quad_perm:[2,3,0,1] row_mask:0xf bank_mask:0xf
	v_max_f32_dpp v185, v185, v185 quad_perm:[2,3,0,1] row_mask:0xf bank_mask:0xf
	v_max_f32_dpp v186, v186, v186 quad_perm:[2,3,0,1] row_mask:0xf bank_mask:0xf
	v_max_f32_dpp v187, v187, v187 quad_perm:[2,3,0,1] row_mask:0xf bank_mask:0xf
	v_max_f32_dpp v184, v184, v184 row_half_mirror row_mask:0xf bank_mask:0xf
	v_max_f32_dpp v185, v185, v185 row_half_mirror row_mask:0xf bank_mask:0xf
	v_max_f32_dpp v186, v186, v186 row_half_mirror row_mask:0xf bank_mask:0xf
	v_max_f32_dpp v187, v187, v187 row_half_mirror row_mask:0xf bank_mask:0xf
	v_max_f32_dpp v184, v184, v184 row_ror:8 row_mask:0xf bank_mask:0xf
	v_max_f32_dpp v185, v185, v185 row_ror:8 row_mask:0xf bank_mask:0xf
	v_max_f32_dpp v186, v186, v186 row_ror:8 row_mask:0xf bank_mask:0xf
	v_max_f32_dpp v187, v187, v187 row_ror:8 row_mask:0xf bank_mask:0xf
	v_max_f32_e32 v184, v172, v184
	v_max_f32_e32 v185, v173, v185
	v_max_f32_e32 v186, v174, v186
	v_max_f32_e32 v187, v175, v187
	v_sub_f32_e32 v180, v172, v184
	v_mov_b32_e32 v172, v184
	v_sub_f32_e32 v181, v173, v185
	v_mov_b32_e32 v173, v185
	v_sub_f32_e32 v182, v174, v186
	v_mov_b32_e32 v174, v186
	v_sub_f32_e32 v183, v175, v187
	v_mov_b32_e32 v175, v187
	v_mul_f32_e32 v180, 0x3fb8aa3b, v180
	v_mul_f32_e32 v181, 0x3fb8aa3b, v181
	v_mul_f32_e32 v182, 0x3fb8aa3b, v182
	v_mul_f32_e32 v183, 0x3fb8aa3b, v183
	v_exp_f32_e32 v180, v180
	v_exp_f32_e32 v181, v181
	v_exp_f32_e32 v182, v182
	v_exp_f32_e32 v183, v183
	v_sub_f32_e32 v76, v76, v172
	v_sub_f32_e32 v77, v77, v173
	v_sub_f32_e32 v78, v78, v174
	v_sub_f32_e32 v79, v79, v175
	v_sub_f32_e32 v84, v84, v172
	v_sub_f32_e32 v85, v85, v173
	v_sub_f32_e32 v86, v86, v174
	v_sub_f32_e32 v87, v87, v175
	v_sub_f32_e32 v88, v88, v172
	v_sub_f32_e32 v89, v89, v173
	v_sub_f32_e32 v90, v90, v174
	v_sub_f32_e32 v91, v91, v175
	v_sub_f32_e32 v96, v96, v172
	v_sub_f32_e32 v97, v97, v173
	v_sub_f32_e32 v98, v98, v174
	v_sub_f32_e32 v99, v99, v175
	v_mul_f32_e32 v76, 0x3fb8aa3b, v76
	v_mul_f32_e32 v77, 0x3fb8aa3b, v77
	v_mul_f32_e32 v78, 0x3fb8aa3b, v78
	v_mul_f32_e32 v79, 0x3fb8aa3b, v79
	v_mul_f32_e32 v84, 0x3fb8aa3b, v84
	v_mul_f32_e32 v85, 0x3fb8aa3b, v85
	v_mul_f32_e32 v86, 0x3fb8aa3b, v86
	v_mul_f32_e32 v87, 0x3fb8aa3b, v87
	v_mul_f32_e32 v88, 0x3fb8aa3b, v88
	v_mul_f32_e32 v89, 0x3fb8aa3b, v89
	v_mul_f32_e32 v90, 0x3fb8aa3b, v90
	v_mul_f32_e32 v91, 0x3fb8aa3b, v91
	v_mul_f32_e32 v96, 0x3fb8aa3b, v96
	v_mul_f32_e32 v97, 0x3fb8aa3b, v97
	v_mul_f32_e32 v98, 0x3fb8aa3b, v98
	v_mul_f32_e32 v99, 0x3fb8aa3b, v99
	v_exp_f32_e32 v76, v76
	v_exp_f32_e32 v77, v77
	v_exp_f32_e32 v78, v78
	v_exp_f32_e32 v79, v79
	v_exp_f32_e32 v84, v84
	v_exp_f32_e32 v85, v85
	v_exp_f32_e32 v86, v86
	v_exp_f32_e32 v87, v87
	v_exp_f32_e32 v88, v88
	v_exp_f32_e32 v89, v89
	v_exp_f32_e32 v90, v90
	v_exp_f32_e32 v91, v91
	v_exp_f32_e32 v96, v96
	v_exp_f32_e32 v97, v97
	v_exp_f32_e32 v98, v98
	v_exp_f32_e32 v99, v99
	s_nop 0
	v_mul_f32_e32 v176, v176, v180
	v_mul_f32_e32 v177, v177, v181
	v_mul_f32_e32 v178, v178, v182
	v_mul_f32_e32 v179, v179, v183
	v_add_f32_e32 v176, v176, v76
	v_add_f32_e32 v177, v177, v77
	v_add_f32_e32 v178, v178, v78
	v_add_f32_e32 v179, v179, v79
	v_add_f32_e32 v176, v176, v84
	v_add_f32_e32 v177, v177, v85
	v_add_f32_e32 v178, v178, v86
	v_add_f32_e32 v179, v179, v87
	v_add_f32_e32 v176, v176, v88
	v_add_f32_e32 v177, v177, v89
	v_add_f32_e32 v178, v178, v90
	v_add_f32_e32 v179, v179, v91
	v_add_f32_e32 v176, v176, v96
	v_add_f32_e32 v177, v177, v97
	v_add_f32_e32 v178, v178, v98
	v_add_f32_e32 v179, v179, v99
	v_cvt_pk_bf16_f32 v80, v76, v76
	ds_write_b16 v188, v80 offset:0
	v_cvt_pk_bf16_f32 v81, v77, v77
	ds_write_b16 v188, v81 offset:160
	v_cvt_pk_bf16_f32 v124, v78, v78
	ds_write_b16 v188, v124 offset:320
	v_cvt_pk_bf16_f32 v126, v79, v79
	ds_write_b16 v188, v126 offset:480
	v_cvt_pk_bf16_f32 v80, v84, v84
	ds_write_b16 v188, v80 offset:32
	v_cvt_pk_bf16_f32 v81, v85, v85
	ds_write_b16 v188, v81 offset:192
	v_cvt_pk_bf16_f32 v124, v86, v86
	ds_write_b16 v188, v124 offset:352
	v_cvt_pk_bf16_f32 v126, v87, v87
	ds_write_b16 v188, v126 offset:512
	v_cvt_pk_bf16_f32 v80, v88, v88
	ds_write_b16 v188, v80 offset:64
	v_cvt_pk_bf16_f32 v81, v89, v89
	ds_write_b16 v188, v81 offset:224
	v_cvt_pk_bf16_f32 v124, v90, v90
	ds_write_b16 v188, v124 offset:384
	v_cvt_pk_bf16_f32 v126, v91, v91
	ds_write_b16 v188, v126 offset:544
	v_cvt_pk_bf16_f32 v80, v96, v96
	ds_write_b16 v188, v80 offset:96
	v_cvt_pk_bf16_f32 v81, v97, v97
	ds_write_b16 v188, v81 offset:256
	v_cvt_pk_bf16_f32 v124, v98, v98
	ds_write_b16 v188, v124 offset:416
	v_cvt_pk_bf16_f32 v126, v99, v99
	ds_write_b16 v188, v126 offset:576
	v_mul_f32_e32 v100, v100, v180
	v_mul_f32_e32 v101, v101, v181
	v_mul_f32_e32 v102, v102, v182
	v_mul_f32_e32 v103, v103, v183
	v_mul_f32_e32 v132, v132, v180
	v_mul_f32_e32 v133, v133, v181
	v_mul_f32_e32 v134, v134, v182
	v_mul_f32_e32 v135, v135, v183
	v_mul_f32_e32 v140, v140, v180
	v_mul_f32_e32 v141, v141, v181
	v_mul_f32_e32 v142, v142, v182
	v_mul_f32_e32 v143, v143, v183
	v_mul_f32_e32 v144, v144, v180
	v_mul_f32_e32 v145, v145, v181
	v_mul_f32_e32 v146, v146, v182
	v_mul_f32_e32 v147, v147, v183
	s_waitcnt lgkmcnt(0)
	ds_read_b128 v[164:167], v191 offset:0
	ds_read_b128 v[168:171], v191 offset:64
	s_waitcnt vmcnt(8)
	s_waitcnt lgkmcnt(0)
	v_mfma_f32_16x16x32_bf16 v[100:103], v[164:167], v[44:47], v[100:103]
	v_mfma_f32_16x16x32_bf16 v[132:135], v[164:167], v[48:51], v[132:135]
	v_mfma_f32_16x16x32_bf16 v[140:143], v[164:167], v[52:55], v[140:143]
	v_mfma_f32_16x16x32_bf16 v[144:147], v[164:167], v[56:59], v[144:147]
	v_mfma_f32_16x16x32_bf16 v[100:103], v[168:171], v[60:63], v[100:103]
	v_mfma_f32_16x16x32_bf16 v[132:135], v[168:171], v[64:67], v[132:135]
	v_mfma_f32_16x16x32_bf16 v[140:143], v[168:171], v[68:71], v[140:143]
	v_mfma_f32_16x16x32_bf16 v[144:147], v[168:171], v[72:75], v[144:147]
	s_nop 3
	s_add_u32 s26, s12, 248
	s_addc_u32 s27, s13, 0
	global_load_dword v148, v192, s[26:27]
	global_load_dword v149, v193, s[26:27]
	global_load_dword v150, v194, s[26:27]
	global_load_dword v151, v195, s[26:27]
	s_add_u32 s26, s12, 248
	s_addc_u32 s27, s13, 0
	global_load_dword v152, v196, s[26:27]
	global_load_dword v153, v197, s[26:27]
	global_load_dword v154, v198, s[26:27]
	global_load_dword v155, v199, s[26:27]
	s_add_u32 s26, s12, 372
	s_addc_u32 s27, s13, 0
	global_load_dword v156, v192, s[26:27]
	global_load_dword v157, v193, s[26:27]
	global_load_dword v158, v194, s[26:27]
	global_load_dword v159, v195, s[26:27]
	s_add_u32 s26, s12, 372
	s_addc_u32 s27, s13, 0
	global_load_dword v160, v196, s[26:27]
	global_load_dword v161, v197, s[26:27]
	global_load_dword v162, v198, s[26:27]
	global_load_dword v163, v199, s[26:27]
	s_add_u32 s8, s6, 2
	s_lshl_b32 s8, s8, 6
	s_add_u32 s8, s8, s7
	s_lshl_b32 s8, s8, 1
	s_add_u32 s24, s18, s8
	s_addc_u32 s25, s19, 0
	global_load_dwordx4 v[44:47], v214, s[24:25]
	global_load_dwordx4 v[48:51], v215, s[24:25]
	global_load_dwordx4 v[52:55], v216, s[24:25]
	global_load_dwordx4 v[56:59], v217, s[24:25]
	s_add_u32 s8, s6, 3
	s_lshl_b32 s8, s8, 6
	s_add_u32 s8, s8, s7
	s_lshl_b32 s8, s8, 1
	s_add_u32 s24, s18, s8
	s_addc_u32 s25, s19, 0
	global_load_dwordx4 v[60:63], v214, s[24:25]
	global_load_dwordx4 v[64:67], v215, s[24:25]
	global_load_dwordx4 v[68:71], v216, s[24:25]
	global_load_dwordx4 v[72:75], v217, s[24:25]
	s_waitcnt vmcnt(24)
	v_mov_b32_e32 v76, 0
	v_mov_b32_e32 v77, 0
	v_mov_b32_e32 v78, 0
	v_mov_b32_e32 v79, 0
	v_mov_b32_e32 v84, 0
	v_mov_b32_e32 v85, 0
	v_mov_b32_e32 v86, 0
	v_mov_b32_e32 v87, 0
	v_mov_b32_e32 v88, 0
	v_mov_b32_e32 v89, 0
	v_mov_b32_e32 v90, 0
	v_mov_b32_e32 v91, 0
	v_mov_b32_e32 v96, 0
	v_mov_b32_e32 v97, 0
	v_mov_b32_e32 v98, 0
	v_mov_b32_e32 v99, 0
	s_nop 1
	v_mfma_f32_16x16x32_bf16 v[76:79], v[4:7], v[12:15], v[76:79]
	v_mfma_f32_16x16x32_bf16 v[76:79], v[8:11], v[16:19], v[76:79]
	v_mfma_f32_16x16x32_bf16 v[84:87], v[4:7], v[20:23], v[84:87]
	v_mfma_f32_16x16x32_bf16 v[84:87], v[8:11], v[24:27], v[84:87]
	v_mfma_f32_16x16x32_bf16 v[88:91], v[4:7], v[28:31], v[88:91]
	v_mfma_f32_16x16x32_bf16 v[88:91], v[8:11], v[32:35], v[88:91]
	v_mfma_f32_16x16x32_bf16 v[96:99], v[4:7], v[36:39], v[96:99]
	v_mfma_f32_16x16x32_bf16 v[96:99], v[8:11], v[40:43], v[96:99]
	s_nop 3
	s_add_u32 s8, s6, 4
	s_lshl_b32 s8, s8, 6
	s_add_u32 s8, s8, s7
	s_lshl_b32 s8, s8, 13
	s_add_u32 s22, s16, s8
	s_addc_u32 s23, s17, 0
	global_load_dwordx4 v[12:15], v130, s[22:23]
	global_load_dwordx4 v[16:19], v130, s[22:23] offset:64
	s_add_u32 s8, s6, 4
	s_lshl_b32 s8, s8, 6
	s_add_u32 s8, s8, s7
	s_add_u32 s8, s8, 16
	s_lshl_b32 s8, s8, 13
	s_add_u32 s22, s16, s8
	s_addc_u32 s23, s17, 0
	global_load_dwordx4 v[20:23], v130, s[22:23]
	global_load_dwordx4 v[24:27], v130, s[22:23] offset:64
	s_add_u32 s8, s6, 5
	s_lshl_b32 s8, s8, 6
	s_add_u32 s8, s8, s7
	s_lshl_b32 s8, s8, 13
	s_add_u32 s22, s16, s8
	s_addc_u32 s23, s17, 0
	global_load_dwordx4 v[28:31], v130, s[22:23]
	global_load_dwordx4 v[32:35], v130, s[22:23] offset:64
	s_add_u32 s8, s6, 5
	s_lshl_b32 s8, s8, 6
	s_add_u32 s8, s8, s7
	s_add_u32 s8, s8, 16
	s_lshl_b32 s8, s8, 13
	s_add_u32 s22, s16, s8
	s_addc_u32 s23, s17, 0
	global_load_dwordx4 v[36:39], v130, s[22:23]
	global_load_dwordx4 v[40:43], v130, s[22:23] offset:64
	s_nop 7
	s_waitcnt vmcnt(16)
	v_mul_f32_e32 v76, 0x3e000000, v76
	v_add_f32_e32 v148, v148, v200
	v_add_f32_e32 v76, v76, v148
	v_mul_f32_e32 v77, 0x3e000000, v77
	v_add_f32_e32 v149, v149, v201
	v_add_f32_e32 v77, v77, v149
	v_mul_f32_e32 v78, 0x3e000000, v78
	v_add_f32_e32 v150, v150, v202
	v_add_f32_e32 v78, v78, v150
	v_mul_f32_e32 v79, 0x3e000000, v79
	v_add_f32_e32 v151, v151, v203
	v_add_f32_e32 v79, v79, v151
	v_mul_f32_e32 v84, 0x3e000000, v84
	v_add_f32_e32 v152, v152, v204
	v_add_f32_e32 v84, v84, v152
	v_mul_f32_e32 v85, 0x3e000000, v85
	v_add_f32_e32 v153, v153, v205
	v_add_f32_e32 v85, v85, v153
	v_mul_f32_e32 v86, 0x3e000000, v86
	v_add_f32_e32 v154, v154, v206
	v_add_f32_e32 v86, v86, v154
	v_mul_f32_e32 v87, 0x3e000000, v87
	v_add_f32_e32 v155, v155, v207
	v_add_f32_e32 v87, v87, v155
	v_mul_f32_e32 v88, 0x3e000000, v88
	v_add_f32_e32 v156, v156, v200
	v_add_f32_e32 v88, v88, v156
	v_mul_f32_e32 v89, 0x3e000000, v89
	v_add_f32_e32 v157, v157, v201
	v_add_f32_e32 v89, v89, v157
	v_mul_f32_e32 v90, 0x3e000000, v90
	v_add_f32_e32 v158, v158, v202
	v_add_f32_e32 v90, v90, v158
	v_mul_f32_e32 v91, 0x3e000000, v91
	v_add_f32_e32 v159, v159, v203
	v_add_f32_e32 v91, v91, v159
	v_mul_f32_e32 v96, 0x3e000000, v96
	v_add_f32_e32 v160, v160, v204
	v_add_f32_e32 v96, v96, v160
	v_mul_f32_e32 v97, 0x3e000000, v97
	v_add_f32_e32 v161, v161, v205
	v_add_f32_e32 v97, v97, v161
	v_mul_f32_e32 v98, 0x3e000000, v98
	v_add_f32_e32 v162, v162, v206
	v_add_f32_e32 v98, v98, v162
	v_mul_f32_e32 v99, 0x3e000000, v99
	v_add_f32_e32 v163, v163, v207
	v_add_f32_e32 v99, v99, v163
	v_max3_f32 v184, v76, v84, v88
	v_max_f32_e32 v184, v184, v96
	v_max3_f32 v185, v77, v85, v89
	v_max_f32_e32 v185, v185, v97
	v_max3_f32 v186, v78, v86, v90
	v_max_f32_e32 v186, v186, v98
	v_max3_f32 v187, v79, v87, v91
	v_max_f32_e32 v187, v187, v99
	s_nop 0
	v_max_f32_dpp v184, v184, v184 quad_perm:[1,0,3,2] row_mask:0xf bank_mask:0xf
	v_max_f32_dpp v185, v185, v185 quad_perm:[1,0,3,2] row_mask:0xf bank_mask:0xf
	v_max_f32_dpp v186, v186, v186 quad_perm:[1,0,3,2] row_mask:0xf bank_mask:0xf
	v_max_f32_dpp v187, v187, v187 quad_perm:[1,0,3,2] row_mask:0xf bank_mask:0xf
	v_max_f32_dpp v184, v184, v184 quad_perm:[2,3,0,1] row_mask:0xf bank_mask:0xf
	v_max_f32_dpp v185, v185, v185 quad_perm:[2,3,0,1] row_mask:0xf bank_mask:0xf
	v_max_f32_dpp v186, v186, v186 quad_perm:[2,3,0,1] row_mask:0xf bank_mask:0xf
	v_max_f32_dpp v187, v187, v187 quad_perm:[2,3,0,1] row_mask:0xf bank_mask:0xf
	v_max_f32_dpp v184, v184, v184 row_half_mirror row_mask:0xf bank_mask:0xf
	v_max_f32_dpp v185, v185, v185 row_half_mirror row_mask:0xf bank_mask:0xf
	v_max_f32_dpp v186, v186, v186 row_half_mirror row_mask:0xf bank_mask:0xf
	v_max_f32_dpp v187, v187, v187 row_half_mirror row_mask:0xf bank_mask:0xf
	v_max_f32_dpp v184, v184, v184 row_ror:8 row_mask:0xf bank_mask:0xf
	v_max_f32_dpp v185, v185, v185 row_ror:8 row_mask:0xf bank_mask:0xf
	v_max_f32_dpp v186, v186, v186 row_ror:8 row_mask:0xf bank_mask:0xf
	v_max_f32_dpp v187, v187, v187 row_ror:8 row_mask:0xf bank_mask:0xf
	v_max_f32_e32 v184, v172, v184
	v_max_f32_e32 v185, v173, v185
	v_max_f32_e32 v186, v174, v186
	v_max_f32_e32 v187, v175, v187
	v_sub_f32_e32 v180, v172, v184
	v_mov_b32_e32 v172, v184
	v_sub_f32_e32 v181, v173, v185
	v_mov_b32_e32 v173, v185
	v_sub_f32_e32 v182, v174, v186
	v_mov_b32_e32 v174, v186
	v_sub_f32_e32 v183, v175, v187
	v_mov_b32_e32 v175, v187
	v_mul_f32_e32 v180, 0x3fb8aa3b, v180
	v_mul_f32_e32 v181, 0x3fb8aa3b, v181
	v_mul_f32_e32 v182, 0x3fb8aa3b, v182
	v_mul_f32_e32 v183, 0x3fb8aa3b, v183
	v_exp_f32_e32 v180, v180
	v_exp_f32_e32 v181, v181
	v_exp_f32_e32 v182, v182
	v_exp_f32_e32 v183, v183
	v_sub_f32_e32 v76, v76, v172
	v_sub_f32_e32 v77, v77, v173
	v_sub_f32_e32 v78, v78, v174
	v_sub_f32_e32 v79, v79, v175
	v_sub_f32_e32 v84, v84, v172
	v_sub_f32_e32 v85, v85, v173
	v_sub_f32_e32 v86, v86, v174
	v_sub_f32_e32 v87, v87, v175
	v_sub_f32_e32 v88, v88, v172
	v_sub_f32_e32 v89, v89, v173
	v_sub_f32_e32 v90, v90, v174
	v_sub_f32_e32 v91, v91, v175
	v_sub_f32_e32 v96, v96, v172
	v_sub_f32_e32 v97, v97, v173
	v_sub_f32_e32 v98, v98, v174
	v_sub_f32_e32 v99, v99, v175
	v_mul_f32_e32 v76, 0x3fb8aa3b, v76
	v_mul_f32_e32 v77, 0x3fb8aa3b, v77
	v_mul_f32_e32 v78, 0x3fb8aa3b, v78
	v_mul_f32_e32 v79, 0x3fb8aa3b, v79
	v_mul_f32_e32 v84, 0x3fb8aa3b, v84
	v_mul_f32_e32 v85, 0x3fb8aa3b, v85
	v_mul_f32_e32 v86, 0x3fb8aa3b, v86
	v_mul_f32_e32 v87, 0x3fb8aa3b, v87
	v_mul_f32_e32 v88, 0x3fb8aa3b, v88
	v_mul_f32_e32 v89, 0x3fb8aa3b, v89
	v_mul_f32_e32 v90, 0x3fb8aa3b, v90
	v_mul_f32_e32 v91, 0x3fb8aa3b, v91
	v_mul_f32_e32 v96, 0x3fb8aa3b, v96
	v_mul_f32_e32 v97, 0x3fb8aa3b, v97
	v_mul_f32_e32 v98, 0x3fb8aa3b, v98
	v_mul_f32_e32 v99, 0x3fb8aa3b, v99
	v_exp_f32_e32 v76, v76
	v_exp_f32_e32 v77, v77
	v_exp_f32_e32 v78, v78
	v_exp_f32_e32 v79, v79
	v_exp_f32_e32 v84, v84
	v_exp_f32_e32 v85, v85
	v_exp_f32_e32 v86, v86
	v_exp_f32_e32 v87, v87
	v_exp_f32_e32 v88, v88
	v_exp_f32_e32 v89, v89
	v_exp_f32_e32 v90, v90
	v_exp_f32_e32 v91, v91
	v_exp_f32_e32 v96, v96
	v_exp_f32_e32 v97, v97
	v_exp_f32_e32 v98, v98
	v_exp_f32_e32 v99, v99
	s_nop 0
	v_mul_f32_e32 v176, v176, v180
	v_mul_f32_e32 v177, v177, v181
	v_mul_f32_e32 v178, v178, v182
	v_mul_f32_e32 v179, v179, v183
	v_add_f32_e32 v176, v176, v76
	v_add_f32_e32 v177, v177, v77
	v_add_f32_e32 v178, v178, v78
	v_add_f32_e32 v179, v179, v79
	v_add_f32_e32 v176, v176, v84
	v_add_f32_e32 v177, v177, v85
	v_add_f32_e32 v178, v178, v86
	v_add_f32_e32 v179, v179, v87
	v_add_f32_e32 v176, v176, v88
	v_add_f32_e32 v177, v177, v89
	v_add_f32_e32 v178, v178, v90
	v_add_f32_e32 v179, v179, v91
	v_add_f32_e32 v176, v176, v96
	v_add_f32_e32 v177, v177, v97
	v_add_f32_e32 v178, v178, v98
	v_add_f32_e32 v179, v179, v99
	v_cvt_pk_bf16_f32 v80, v76, v76
	ds_write_b16 v188, v80 offset:0
	v_cvt_pk_bf16_f32 v81, v77, v77
	ds_write_b16 v188, v81 offset:160
	v_cvt_pk_bf16_f32 v124, v78, v78
	ds_write_b16 v188, v124 offset:320
	v_cvt_pk_bf16_f32 v126, v79, v79
	ds_write_b16 v188, v126 offset:480
	v_cvt_pk_bf16_f32 v80, v84, v84
	ds_write_b16 v188, v80 offset:32
	v_cvt_pk_bf16_f32 v81, v85, v85
	ds_write_b16 v188, v81 offset:192
	v_cvt_pk_bf16_f32 v124, v86, v86
	ds_write_b16 v188, v124 offset:352
	v_cvt_pk_bf16_f32 v126, v87, v87
	ds_write_b16 v188, v126 offset:512
	v_cvt_pk_bf16_f32 v80, v88, v88
	ds_write_b16 v188, v80 offset:64
	v_cvt_pk_bf16_f32 v81, v89, v89
	ds_write_b16 v188, v81 offset:224
	v_cvt_pk_bf16_f32 v124, v90, v90
	ds_write_b16 v188, v124 offset:384
	v_cvt_pk_bf16_f32 v126, v91, v91
	ds_write_b16 v188, v126 offset:544
	v_cvt_pk_bf16_f32 v80, v96, v96
	ds_write_b16 v188, v80 offset:96
	v_cvt_pk_bf16_f32 v81, v97, v97
	ds_write_b16 v188, v81 offset:256
	v_cvt_pk_bf16_f32 v124, v98, v98
	ds_write_b16 v188, v124 offset:416
	v_cvt_pk_bf16_f32 v126, v99, v99
	ds_write_b16 v188, v126 offset:576
	v_mul_f32_e32 v100, v100, v180
	v_mul_f32_e32 v101, v101, v181
	v_mul_f32_e32 v102, v102, v182
	v_mul_f32_e32 v103, v103, v183
	v_mul_f32_e32 v132, v132, v180
	v_mul_f32_e32 v133, v133, v181
	v_mul_f32_e32 v134, v134, v182
	v_mul_f32_e32 v135, v135, v183
	v_mul_f32_e32 v140, v140, v180
	v_mul_f32_e32 v141, v141, v181
	v_mul_f32_e32 v142, v142, v182
	v_mul_f32_e32 v143, v143, v183
	v_mul_f32_e32 v144, v144, v180
	v_mul_f32_e32 v145, v145, v181
	v_mul_f32_e32 v146, v146, v182
	v_mul_f32_e32 v147, v147, v183
	s_waitcnt lgkmcnt(0)
	ds_read_b128 v[164:167], v191 offset:0
	ds_read_b128 v[168:171], v191 offset:64
	s_waitcnt vmcnt(8)
	s_waitcnt lgkmcnt(0)
	v_mfma_f32_16x16x32_bf16 v[100:103], v[164:167], v[44:47], v[100:103]
	v_mfma_f32_16x16x32_bf16 v[132:135], v[164:167], v[48:51], v[132:135]
	v_mfma_f32_16x16x32_bf16 v[140:143], v[164:167], v[52:55], v[140:143]
	v_mfma_f32_16x16x32_bf16 v[144:147], v[164:167], v[56:59], v[144:147]
	v_mfma_f32_16x16x32_bf16 v[100:103], v[168:171], v[60:63], v[100:103]
	v_mfma_f32_16x16x32_bf16 v[132:135], v[168:171], v[64:67], v[132:135]
	v_mfma_f32_16x16x32_bf16 v[140:143], v[168:171], v[68:71], v[140:143]
	v_mfma_f32_16x16x32_bf16 v[144:147], v[168:171], v[72:75], v[144:147]
	s_nop 3
	s_add_u32 s26, s12, 496
	s_addc_u32 s27, s13, 0
	global_load_dword v148, v192, s[26:27]
	global_load_dword v149, v193, s[26:27]
	global_load_dword v150, v194, s[26:27]
	global_load_dword v151, v195, s[26:27]
	s_add_u32 s26, s12, 496
	s_addc_u32 s27, s13, 0
	global_load_dword v152, v196, s[26:27]
	global_load_dword v153, v197, s[26:27]
	global_load_dword v154, v198, s[26:27]
	global_load_dword v155, v199, s[26:27]
	s_add_u32 s26, s12, 620
	s_addc_u32 s27, s13, 0
	global_load_dword v156, v192, s[26:27]
	global_load_dword v157, v193, s[26:27]
	global_load_dword v158, v194, s[26:27]
	global_load_dword v159, v195, s[26:27]
	s_add_u32 s26, s12, 620
	s_addc_u32 s27, s13, 0
	global_load_dword v160, v196, s[26:27]
	global_load_dword v161, v197, s[26:27]
	global_load_dword v162, v198, s[26:27]
	global_load_dword v163, v199, s[26:27]
	s_add_u32 s8, s6, 4
	s_lshl_b32 s8, s8, 6
	s_add_u32 s8, s8, s7
	s_lshl_b32 s8, s8, 1
	s_add_u32 s24, s18, s8
	s_addc_u32 s25, s19, 0
	global_load_dwordx4 v[44:47], v214, s[24:25]
	global_load_dwordx4 v[48:51], v215, s[24:25]
	global_load_dwordx4 v[52:55], v216, s[24:25]
	global_load_dwordx4 v[56:59], v217, s[24:25]
	s_add_u32 s8, s6, 5
	s_lshl_b32 s8, s8, 6
	s_add_u32 s8, s8, s7
	s_lshl_b32 s8, s8, 1
	s_add_u32 s24, s18, s8
	s_addc_u32 s25, s19, 0
	global_load_dwordx4 v[60:63], v214, s[24:25]
	global_load_dwordx4 v[64:67], v215, s[24:25]
	global_load_dwordx4 v[68:71], v216, s[24:25]
	global_load_dwordx4 v[72:75], v217, s[24:25]
	s_waitcnt vmcnt(24)
	v_mov_b32_e32 v76, 0
	v_mov_b32_e32 v77, 0
	v_mov_b32_e32 v78, 0
	v_mov_b32_e32 v79, 0
	v_mov_b32_e32 v84, 0
	v_mov_b32_e32 v85, 0
	v_mov_b32_e32 v86, 0
	v_mov_b32_e32 v87, 0
	v_mov_b32_e32 v88, 0
	v_mov_b32_e32 v89, 0
	v_mov_b32_e32 v90, 0
	v_mov_b32_e32 v91, 0
	v_mov_b32_e32 v96, 0
	v_mov_b32_e32 v97, 0
	v_mov_b32_e32 v98, 0
	v_mov_b32_e32 v99, 0
	s_nop 1
	v_mfma_f32_16x16x32_bf16 v[76:79], v[4:7], v[12:15], v[76:79]
	v_mfma_f32_16x16x32_bf16 v[76:79], v[8:11], v[16:19], v[76:79]
	v_mfma_f32_16x16x32_bf16 v[84:87], v[4:7], v[20:23], v[84:87]
	v_mfma_f32_16x16x32_bf16 v[84:87], v[8:11], v[24:27], v[84:87]
	v_mfma_f32_16x16x32_bf16 v[88:91], v[4:7], v[28:31], v[88:91]
	v_mfma_f32_16x16x32_bf16 v[88:91], v[8:11], v[32:35], v[88:91]
	v_mfma_f32_16x16x32_bf16 v[96:99], v[4:7], v[36:39], v[96:99]
	v_mfma_f32_16x16x32_bf16 v[96:99], v[8:11], v[40:43], v[96:99]
	s_nop 3
	s_add_u32 s8, s6, 6
	s_lshl_b32 s8, s8, 6
	s_add_u32 s8, s8, s7
	s_lshl_b32 s8, s8, 13
	s_add_u32 s22, s16, s8
	s_addc_u32 s23, s17, 0
	global_load_dwordx4 v[12:15], v130, s[22:23]
	global_load_dwordx4 v[16:19], v130, s[22:23] offset:64
	s_add_u32 s8, s6, 6
	s_lshl_b32 s8, s8, 6
	s_add_u32 s8, s8, s7
	s_add_u32 s8, s8, 16
	s_lshl_b32 s8, s8, 13
	s_add_u32 s22, s16, s8
	s_addc_u32 s23, s17, 0
	global_load_dwordx4 v[20:23], v130, s[22:23]
	global_load_dwordx4 v[24:27], v130, s[22:23] offset:64
	s_add_u32 s8, s6, 7
	s_lshl_b32 s8, s8, 6
	s_add_u32 s8, s8, s7
	s_lshl_b32 s8, s8, 13
	s_add_u32 s22, s16, s8
	s_addc_u32 s23, s17, 0
	global_load_dwordx4 v[28:31], v130, s[22:23]
	global_load_dwordx4 v[32:35], v130, s[22:23] offset:64
	s_add_u32 s8, s6, 7
	s_lshl_b32 s8, s8, 6
	s_add_u32 s8, s8, s7
	s_add_u32 s8, s8, 16
	s_lshl_b32 s8, s8, 13
	s_add_u32 s22, s16, s8
	s_addc_u32 s23, s17, 0
	global_load_dwordx4 v[36:39], v130, s[22:23]
	global_load_dwordx4 v[40:43], v130, s[22:23] offset:64
	s_nop 7
	s_waitcnt vmcnt(16)
	v_mul_f32_e32 v76, 0x3e000000, v76
	v_add_f32_e32 v148, v148, v200
	v_add_f32_e32 v76, v76, v148
	v_mul_f32_e32 v77, 0x3e000000, v77
	v_add_f32_e32 v149, v149, v201
	v_add_f32_e32 v77, v77, v149
	v_mul_f32_e32 v78, 0x3e000000, v78
	v_add_f32_e32 v150, v150, v202
	v_add_f32_e32 v78, v78, v150
	v_mul_f32_e32 v79, 0x3e000000, v79
	v_add_f32_e32 v151, v151, v203
	v_add_f32_e32 v79, v79, v151
	v_mul_f32_e32 v84, 0x3e000000, v84
	v_add_f32_e32 v152, v152, v204
	v_add_f32_e32 v84, v84, v152
	v_mul_f32_e32 v85, 0x3e000000, v85
	v_add_f32_e32 v153, v153, v205
	v_add_f32_e32 v85, v85, v153
	v_mul_f32_e32 v86, 0x3e000000, v86
	v_add_f32_e32 v154, v154, v206
	v_add_f32_e32 v86, v86, v154
	v_mul_f32_e32 v87, 0x3e000000, v87
	v_add_f32_e32 v155, v155, v207
	v_add_f32_e32 v87, v87, v155
	v_mul_f32_e32 v88, 0x3e000000, v88
	v_add_f32_e32 v156, v156, v200
	v_add_f32_e32 v88, v88, v156
	v_mul_f32_e32 v89, 0x3e000000, v89
	v_add_f32_e32 v157, v157, v201
	v_add_f32_e32 v89, v89, v157
	v_mul_f32_e32 v90, 0x3e000000, v90
	v_add_f32_e32 v158, v158, v202
	v_add_f32_e32 v90, v90, v158
	v_mul_f32_e32 v91, 0x3e000000, v91
	v_add_f32_e32 v159, v159, v203
	v_add_f32_e32 v91, v91, v159
	v_mul_f32_e32 v96, 0x3e000000, v96
	v_add_f32_e32 v160, v160, v204
	v_add_f32_e32 v96, v96, v160
	v_mul_f32_e32 v97, 0x3e000000, v97
	v_add_f32_e32 v161, v161, v205
	v_add_f32_e32 v97, v97, v161
	v_mul_f32_e32 v98, 0x3e000000, v98
	v_add_f32_e32 v162, v162, v206
	v_add_f32_e32 v98, v98, v162
	v_mul_f32_e32 v99, 0x3e000000, v99
	v_add_f32_e32 v163, v163, v207
	v_add_f32_e32 v99, v99, v163
	v_max3_f32 v184, v76, v84, v88
	v_max_f32_e32 v184, v184, v96
	v_max3_f32 v185, v77, v85, v89
	v_max_f32_e32 v185, v185, v97
	v_max3_f32 v186, v78, v86, v90
	v_max_f32_e32 v186, v186, v98
	v_max3_f32 v187, v79, v87, v91
	v_max_f32_e32 v187, v187, v99
	s_nop 0
	v_max_f32_dpp v184, v184, v184 quad_perm:[1,0,3,2] row_mask:0xf bank_mask:0xf
	v_max_f32_dpp v185, v185, v185 quad_perm:[1,0,3,2] row_mask:0xf bank_mask:0xf
	v_max_f32_dpp v186, v186, v186 quad_perm:[1,0,3,2] row_mask:0xf bank_mask:0xf
	v_max_f32_dpp v187, v187, v187 quad_perm:[1,0,3,2] row_mask:0xf bank_mask:0xf
	v_max_f32_dpp v184, v184, v184 quad_perm:[2,3,0,1] row_mask:0xf bank_mask:0xf
	v_max_f32_dpp v185, v185, v185 quad_perm:[2,3,0,1] row_mask:0xf bank_mask:0xf
	v_max_f32_dpp v186, v186, v186 quad_perm:[2,3,0,1] row_mask:0xf bank_mask:0xf
	v_max_f32_dpp v187, v187, v187 quad_perm:[2,3,0,1] row_mask:0xf bank_mask:0xf
	v_max_f32_dpp v184, v184, v184 row_half_mirror row_mask:0xf bank_mask:0xf
	v_max_f32_dpp v185, v185, v185 row_half_mirror row_mask:0xf bank_mask:0xf
	v_max_f32_dpp v186, v186, v186 row_half_mirror row_mask:0xf bank_mask:0xf
	v_max_f32_dpp v187, v187, v187 row_half_mirror row_mask:0xf bank_mask:0xf
	v_max_f32_dpp v184, v184, v184 row_ror:8 row_mask:0xf bank_mask:0xf
	v_max_f32_dpp v185, v185, v185 row_ror:8 row_mask:0xf bank_mask:0xf
	v_max_f32_dpp v186, v186, v186 row_ror:8 row_mask:0xf bank_mask:0xf
	v_max_f32_dpp v187, v187, v187 row_ror:8 row_mask:0xf bank_mask:0xf
	v_max_f32_e32 v184, v172, v184
	v_max_f32_e32 v185, v173, v185
	v_max_f32_e32 v186, v174, v186
	v_max_f32_e32 v187, v175, v187
	v_sub_f32_e32 v180, v172, v184
	v_mov_b32_e32 v172, v184
	v_sub_f32_e32 v181, v173, v185
	v_mov_b32_e32 v173, v185
	v_sub_f32_e32 v182, v174, v186
	v_mov_b32_e32 v174, v186
	v_sub_f32_e32 v183, v175, v187
	v_mov_b32_e32 v175, v187
	v_mul_f32_e32 v180, 0x3fb8aa3b, v180
	v_mul_f32_e32 v181, 0x3fb8aa3b, v181
	v_mul_f32_e32 v182, 0x3fb8aa3b, v182
	v_mul_f32_e32 v183, 0x3fb8aa3b, v183
	v_exp_f32_e32 v180, v180
	v_exp_f32_e32 v181, v181
	v_exp_f32_e32 v182, v182
	v_exp_f32_e32 v183, v183
	v_sub_f32_e32 v76, v76, v172
	v_sub_f32_e32 v77, v77, v173
	v_sub_f32_e32 v78, v78, v174
	v_sub_f32_e32 v79, v79, v175
	v_sub_f32_e32 v84, v84, v172
	v_sub_f32_e32 v85, v85, v173
	v_sub_f32_e32 v86, v86, v174
	v_sub_f32_e32 v87, v87, v175
	v_sub_f32_e32 v88, v88, v172
	v_sub_f32_e32 v89, v89, v173
	v_sub_f32_e32 v90, v90, v174
	v_sub_f32_e32 v91, v91, v175
	v_sub_f32_e32 v96, v96, v172
	v_sub_f32_e32 v97, v97, v173
	v_sub_f32_e32 v98, v98, v174
	v_sub_f32_e32 v99, v99, v175
	v_mul_f32_e32 v76, 0x3fb8aa3b, v76
	v_mul_f32_e32 v77, 0x3fb8aa3b, v77
	v_mul_f32_e32 v78, 0x3fb8aa3b, v78
	v_mul_f32_e32 v79, 0x3fb8aa3b, v79
	v_mul_f32_e32 v84, 0x3fb8aa3b, v84
	v_mul_f32_e32 v85, 0x3fb8aa3b, v85
	v_mul_f32_e32 v86, 0x3fb8aa3b, v86
	v_mul_f32_e32 v87, 0x3fb8aa3b, v87
	v_mul_f32_e32 v88, 0x3fb8aa3b, v88
	v_mul_f32_e32 v89, 0x3fb8aa3b, v89
	v_mul_f32_e32 v90, 0x3fb8aa3b, v90
	v_mul_f32_e32 v91, 0x3fb8aa3b, v91
	v_mul_f32_e32 v96, 0x3fb8aa3b, v96
	v_mul_f32_e32 v97, 0x3fb8aa3b, v97
	v_mul_f32_e32 v98, 0x3fb8aa3b, v98
	v_mul_f32_e32 v99, 0x3fb8aa3b, v99
	v_exp_f32_e32 v76, v76
	v_exp_f32_e32 v77, v77
	v_exp_f32_e32 v78, v78
	v_exp_f32_e32 v79, v79
	v_exp_f32_e32 v84, v84
	v_exp_f32_e32 v85, v85
	v_exp_f32_e32 v86, v86
	v_exp_f32_e32 v87, v87
	v_exp_f32_e32 v88, v88
	v_exp_f32_e32 v89, v89
	v_exp_f32_e32 v90, v90
	v_exp_f32_e32 v91, v91
	v_exp_f32_e32 v96, v96
	v_exp_f32_e32 v97, v97
	v_exp_f32_e32 v98, v98
	v_exp_f32_e32 v99, v99
	s_nop 0
	v_mul_f32_e32 v176, v176, v180
	v_mul_f32_e32 v177, v177, v181
	v_mul_f32_e32 v178, v178, v182
	v_mul_f32_e32 v179, v179, v183
	v_add_f32_e32 v176, v176, v76
	v_add_f32_e32 v177, v177, v77
	v_add_f32_e32 v178, v178, v78
	v_add_f32_e32 v179, v179, v79
	v_add_f32_e32 v176, v176, v84
	v_add_f32_e32 v177, v177, v85
	v_add_f32_e32 v178, v178, v86
	v_add_f32_e32 v179, v179, v87
	v_add_f32_e32 v176, v176, v88
	v_add_f32_e32 v177, v177, v89
	v_add_f32_e32 v178, v178, v90
	v_add_f32_e32 v179, v179, v91
	v_add_f32_e32 v176, v176, v96
	v_add_f32_e32 v177, v177, v97
	v_add_f32_e32 v178, v178, v98
	v_add_f32_e32 v179, v179, v99
	v_cvt_pk_bf16_f32 v80, v76, v76
	ds_write_b16 v188, v80 offset:0
	v_cvt_pk_bf16_f32 v81, v77, v77
	ds_write_b16 v188, v81 offset:160
	v_cvt_pk_bf16_f32 v124, v78, v78
	ds_write_b16 v188, v124 offset:320
	v_cvt_pk_bf16_f32 v126, v79, v79
	ds_write_b16 v188, v126 offset:480
	v_cvt_pk_bf16_f32 v80, v84, v84
	ds_write_b16 v188, v80 offset:32
	v_cvt_pk_bf16_f32 v81, v85, v85
	ds_write_b16 v188, v81 offset:192
	v_cvt_pk_bf16_f32 v124, v86, v86
	ds_write_b16 v188, v124 offset:352
	v_cvt_pk_bf16_f32 v126, v87, v87
	ds_write_b16 v188, v126 offset:512
	v_cvt_pk_bf16_f32 v80, v88, v88
	ds_write_b16 v188, v80 offset:64
	v_cvt_pk_bf16_f32 v81, v89, v89
	ds_write_b16 v188, v81 offset:224
	v_cvt_pk_bf16_f32 v124, v90, v90
	ds_write_b16 v188, v124 offset:384
	v_cvt_pk_bf16_f32 v126, v91, v91
	ds_write_b16 v188, v126 offset:544
	v_cvt_pk_bf16_f32 v80, v96, v96
	ds_write_b16 v188, v80 offset:96
	v_cvt_pk_bf16_f32 v81, v97, v97
	ds_write_b16 v188, v81 offset:256
	v_cvt_pk_bf16_f32 v124, v98, v98
	ds_write_b16 v188, v124 offset:416
	v_cvt_pk_bf16_f32 v126, v99, v99
	ds_write_b16 v188, v126 offset:576
	v_mul_f32_e32 v100, v100, v180
	v_mul_f32_e32 v101, v101, v181
	v_mul_f32_e32 v102, v102, v182
	v_mul_f32_e32 v103, v103, v183
	v_mul_f32_e32 v132, v132, v180
	v_mul_f32_e32 v133, v133, v181
	v_mul_f32_e32 v134, v134, v182
	v_mul_f32_e32 v135, v135, v183
	v_mul_f32_e32 v140, v140, v180
	v_mul_f32_e32 v141, v141, v181
	v_mul_f32_e32 v142, v142, v182
	v_mul_f32_e32 v143, v143, v183
	v_mul_f32_e32 v144, v144, v180
	v_mul_f32_e32 v145, v145, v181
	v_mul_f32_e32 v146, v146, v182
	v_mul_f32_e32 v147, v147, v183
	s_waitcnt lgkmcnt(0)
	ds_read_b128 v[164:167], v191 offset:0
	ds_read_b128 v[168:171], v191 offset:64
	s_waitcnt vmcnt(8)
	s_waitcnt lgkmcnt(0)
	v_mfma_f32_16x16x32_bf16 v[100:103], v[164:167], v[44:47], v[100:103]
	v_mfma_f32_16x16x32_bf16 v[132:135], v[164:167], v[48:51], v[132:135]
	v_mfma_f32_16x16x32_bf16 v[140:143], v[164:167], v[52:55], v[140:143]
	v_mfma_f32_16x16x32_bf16 v[144:147], v[164:167], v[56:59], v[144:147]
	v_mfma_f32_16x16x32_bf16 v[100:103], v[168:171], v[60:63], v[100:103]
	v_mfma_f32_16x16x32_bf16 v[132:135], v[168:171], v[64:67], v[132:135]
	v_mfma_f32_16x16x32_bf16 v[140:143], v[168:171], v[68:71], v[140:143]
	v_mfma_f32_16x16x32_bf16 v[144:147], v[168:171], v[72:75], v[144:147]
	s_nop 3
	s_add_u32 s26, s12, 744
	s_addc_u32 s27, s13, 0
	global_load_dword v148, v192, s[26:27]
	global_load_dword v149, v193, s[26:27]
	global_load_dword v150, v194, s[26:27]
	global_load_dword v151, v195, s[26:27]
	s_add_u32 s26, s12, 744
	s_addc_u32 s27, s13, 0
	global_load_dword v152, v196, s[26:27]
	global_load_dword v153, v197, s[26:27]
	global_load_dword v154, v198, s[26:27]
	global_load_dword v155, v199, s[26:27]
	s_add_u32 s26, s12, 868
	s_addc_u32 s27, s13, 0
	global_load_dword v156, v192, s[26:27]
	global_load_dword v157, v193, s[26:27]
	global_load_dword v158, v194, s[26:27]
	global_load_dword v159, v195, s[26:27]
	s_add_u32 s26, s12, 868
	s_addc_u32 s27, s13, 0
	global_load_dword v160, v196, s[26:27]
	global_load_dword v161, v197, s[26:27]
	global_load_dword v162, v198, s[26:27]
	global_load_dword v163, v199, s[26:27]
	s_add_u32 s8, s6, 6
	s_lshl_b32 s8, s8, 6
	s_add_u32 s8, s8, s7
	s_lshl_b32 s8, s8, 1
	s_add_u32 s24, s18, s8
	s_addc_u32 s25, s19, 0
	global_load_dwordx4 v[44:47], v214, s[24:25]
	global_load_dwordx4 v[48:51], v215, s[24:25]
	global_load_dwordx4 v[52:55], v216, s[24:25]
	global_load_dwordx4 v[56:59], v217, s[24:25]
	s_add_u32 s8, s6, 7
	s_lshl_b32 s8, s8, 6
	s_add_u32 s8, s8, s7
	s_lshl_b32 s8, s8, 1
	s_add_u32 s24, s18, s8
	s_addc_u32 s25, s19, 0
	global_load_dwordx4 v[60:63], v214, s[24:25]
	global_load_dwordx4 v[64:67], v215, s[24:25]
	global_load_dwordx4 v[68:71], v216, s[24:25]
	global_load_dwordx4 v[72:75], v217, s[24:25]
	s_waitcnt vmcnt(24)
	v_mov_b32_e32 v76, 0
	v_mov_b32_e32 v77, 0
	v_mov_b32_e32 v78, 0
	v_mov_b32_e32 v79, 0
	v_mov_b32_e32 v84, 0
	v_mov_b32_e32 v85, 0
	v_mov_b32_e32 v86, 0
	v_mov_b32_e32 v87, 0
	v_mov_b32_e32 v88, 0
	v_mov_b32_e32 v89, 0
	v_mov_b32_e32 v90, 0
	v_mov_b32_e32 v91, 0
	v_mov_b32_e32 v96, 0
	v_mov_b32_e32 v97, 0
	v_mov_b32_e32 v98, 0
	v_mov_b32_e32 v99, 0
	s_nop 1
	v_mfma_f32_16x16x32_bf16 v[76:79], v[4:7], v[12:15], v[76:79]
	v_mfma_f32_16x16x32_bf16 v[76:79], v[8:11], v[16:19], v[76:79]
	v_mfma_f32_16x16x32_bf16 v[84:87], v[4:7], v[20:23], v[84:87]
	v_mfma_f32_16x16x32_bf16 v[84:87], v[8:11], v[24:27], v[84:87]
	v_mfma_f32_16x16x32_bf16 v[88:91], v[4:7], v[28:31], v[88:91]
	v_mfma_f32_16x16x32_bf16 v[88:91], v[8:11], v[32:35], v[88:91]
	v_mfma_f32_16x16x32_bf16 v[96:99], v[4:7], v[36:39], v[96:99]
	v_mfma_f32_16x16x32_bf16 v[96:99], v[8:11], v[40:43], v[96:99]
	s_nop 3
	ds_read_b128 v[12:15], v136 offset:0
	ds_read_b128 v[16:19], v136 offset:64
	ds_read_b128 v[20:23], v136 offset:2304
	ds_read_b128 v[24:27], v136 offset:2368
	ds_read_b128 v[28:31], v136 offset:4608
	ds_read_b128 v[32:35], v136 offset:4672
	ds_read_b128 v[36:39], v136 offset:6912
	ds_read_b128 v[40:43], v136 offset:6976
	s_nop 7
	s_waitcnt vmcnt(8)
	v_mul_f32_e32 v76, 0x3e000000, v76
	v_add_f32_e32 v148, v148, v200
	v_add_f32_e32 v76, v76, v148
	v_mul_f32_e32 v77, 0x3e000000, v77
	v_add_f32_e32 v149, v149, v201
	v_add_f32_e32 v77, v77, v149
	v_mul_f32_e32 v78, 0x3e000000, v78
	v_add_f32_e32 v150, v150, v202
	v_add_f32_e32 v78, v78, v150
	v_mul_f32_e32 v79, 0x3e000000, v79
	v_add_f32_e32 v151, v151, v203
	v_add_f32_e32 v79, v79, v151
	v_mul_f32_e32 v84, 0x3e000000, v84
	v_add_f32_e32 v152, v152, v204
	v_add_f32_e32 v84, v84, v152
	v_mul_f32_e32 v85, 0x3e000000, v85
	v_add_f32_e32 v153, v153, v205
	v_add_f32_e32 v85, v85, v153
	v_mul_f32_e32 v86, 0x3e000000, v86
	v_add_f32_e32 v154, v154, v206
	v_add_f32_e32 v86, v86, v154
	v_mul_f32_e32 v87, 0x3e000000, v87
	v_add_f32_e32 v155, v155, v207
	v_add_f32_e32 v87, v87, v155
	v_mul_f32_e32 v88, 0x3e000000, v88
	v_add_f32_e32 v156, v156, v200
	v_add_f32_e32 v88, v88, v156
	v_mul_f32_e32 v89, 0x3e000000, v89
	v_add_f32_e32 v157, v157, v201
	v_add_f32_e32 v89, v89, v157
	v_mul_f32_e32 v90, 0x3e000000, v90
	v_add_f32_e32 v158, v158, v202
	v_add_f32_e32 v90, v90, v158
	v_mul_f32_e32 v91, 0x3e000000, v91
	v_add_f32_e32 v159, v159, v203
	v_add_f32_e32 v91, v91, v159
	v_mul_f32_e32 v96, 0x3e000000, v96
	v_add_f32_e32 v160, v160, v204
	v_add_f32_e32 v96, v96, v160
	v_mul_f32_e32 v97, 0x3e000000, v97
	v_add_f32_e32 v161, v161, v205
	v_add_f32_e32 v97, v97, v161
	v_mul_f32_e32 v98, 0x3e000000, v98
	v_add_f32_e32 v162, v162, v206
	v_add_f32_e32 v98, v98, v162
	v_mul_f32_e32 v99, 0x3e000000, v99
	v_add_f32_e32 v163, v163, v207
	v_add_f32_e32 v99, v99, v163
	v_max3_f32 v184, v76, v84, v88
	v_max_f32_e32 v184, v184, v96
	v_max3_f32 v185, v77, v85, v89
	v_max_f32_e32 v185, v185, v97
	v_max3_f32 v186, v78, v86, v90
	v_max_f32_e32 v186, v186, v98
	v_max3_f32 v187, v79, v87, v91
	v_max_f32_e32 v187, v187, v99
	s_nop 0
	v_max_f32_dpp v184, v184, v184 quad_perm:[1,0,3,2] row_mask:0xf bank_mask:0xf
	v_max_f32_dpp v185, v185, v185 quad_perm:[1,0,3,2] row_mask:0xf bank_mask:0xf
	v_max_f32_dpp v186, v186, v186 quad_perm:[1,0,3,2] row_mask:0xf bank_mask:0xf
	v_max_f32_dpp v187, v187, v187 quad_perm:[1,0,3,2] row_mask:0xf bank_mask:0xf
	v_max_f32_dpp v184, v184, v184 quad_perm:[2,3,0,1] row_mask:0xf bank_mask:0xf
	v_max_f32_dpp v185, v185, v185 quad_perm:[2,3,0,1] row_mask:0xf bank_mask:0xf
	v_max_f32_dpp v186, v186, v186 quad_perm:[2,3,0,1] row_mask:0xf bank_mask:0xf
	v_max_f32_dpp v187, v187, v187 quad_perm:[2,3,0,1] row_mask:0xf bank_mask:0xf
	v_max_f32_dpp v184, v184, v184 row_half_mirror row_mask:0xf bank_mask:0xf
	v_max_f32_dpp v185, v185, v185 row_half_mirror row_mask:0xf bank_mask:0xf
	v_max_f32_dpp v186, v186, v186 row_half_mirror row_mask:0xf bank_mask:0xf
	v_max_f32_dpp v187, v187, v187 row_half_mirror row_mask:0xf bank_mask:0xf
	v_max_f32_dpp v184, v184, v184 row_ror:8 row_mask:0xf bank_mask:0xf
	v_max_f32_dpp v185, v185, v185 row_ror:8 row_mask:0xf bank_mask:0xf
	v_max_f32_dpp v186, v186, v186 row_ror:8 row_mask:0xf bank_mask:0xf
	v_max_f32_dpp v187, v187, v187 row_ror:8 row_mask:0xf bank_mask:0xf
	v_max_f32_e32 v184, v172, v184
	v_max_f32_e32 v185, v173, v185
	v_max_f32_e32 v186, v174, v186
	v_max_f32_e32 v187, v175, v187
	v_sub_f32_e32 v180, v172, v184
	v_mov_b32_e32 v172, v184
	v_sub_f32_e32 v181, v173, v185
	v_mov_b32_e32 v173, v185
	v_sub_f32_e32 v182, v174, v186
	v_mov_b32_e32 v174, v186
	v_sub_f32_e32 v183, v175, v187
	v_mov_b32_e32 v175, v187
	v_mul_f32_e32 v180, 0x3fb8aa3b, v180
	v_mul_f32_e32 v181, 0x3fb8aa3b, v181
	v_mul_f32_e32 v182, 0x3fb8aa3b, v182
	v_mul_f32_e32 v183, 0x3fb8aa3b, v183
	v_exp_f32_e32 v180, v180
	v_exp_f32_e32 v181, v181
	v_exp_f32_e32 v182, v182
	v_exp_f32_e32 v183, v183
	v_sub_f32_e32 v76, v76, v172
	v_sub_f32_e32 v77, v77, v173
	v_sub_f32_e32 v78, v78, v174
	v_sub_f32_e32 v79, v79, v175
	v_sub_f32_e32 v84, v84, v172
	v_sub_f32_e32 v85, v85, v173
	v_sub_f32_e32 v86, v86, v174
	v_sub_f32_e32 v87, v87, v175
	v_sub_f32_e32 v88, v88, v172
	v_sub_f32_e32 v89, v89, v173
	v_sub_f32_e32 v90, v90, v174
	v_sub_f32_e32 v91, v91, v175
	v_sub_f32_e32 v96, v96, v172
	v_sub_f32_e32 v97, v97, v173
	v_sub_f32_e32 v98, v98, v174
	v_sub_f32_e32 v99, v99, v175
	v_mul_f32_e32 v76, 0x3fb8aa3b, v76
	v_mul_f32_e32 v77, 0x3fb8aa3b, v77
	v_mul_f32_e32 v78, 0x3fb8aa3b, v78
	v_mul_f32_e32 v79, 0x3fb8aa3b, v79
	v_mul_f32_e32 v84, 0x3fb8aa3b, v84
	v_mul_f32_e32 v85, 0x3fb8aa3b, v85
	v_mul_f32_e32 v86, 0x3fb8aa3b, v86
	v_mul_f32_e32 v87, 0x3fb8aa3b, v87
	v_mul_f32_e32 v88, 0x3fb8aa3b, v88
	v_mul_f32_e32 v89, 0x3fb8aa3b, v89
	v_mul_f32_e32 v90, 0x3fb8aa3b, v90
	v_mul_f32_e32 v91, 0x3fb8aa3b, v91
	v_mul_f32_e32 v96, 0x3fb8aa3b, v96
	v_mul_f32_e32 v97, 0x3fb8aa3b, v97
	v_mul_f32_e32 v98, 0x3fb8aa3b, v98
	v_mul_f32_e32 v99, 0x3fb8aa3b, v99
	v_exp_f32_e32 v76, v76
	v_exp_f32_e32 v77, v77
	v_exp_f32_e32 v78, v78
	v_exp_f32_e32 v79, v79
	v_exp_f32_e32 v84, v84
	v_exp_f32_e32 v85, v85
	v_exp_f32_e32 v86, v86
	v_exp_f32_e32 v87, v87
	v_exp_f32_e32 v88, v88
	v_exp_f32_e32 v89, v89
	v_exp_f32_e32 v90, v90
	v_exp_f32_e32 v91, v91
	v_exp_f32_e32 v96, v96
	v_exp_f32_e32 v97, v97
	v_exp_f32_e32 v98, v98
	v_exp_f32_e32 v99, v99
	s_nop 0
	v_mul_f32_e32 v176, v176, v180
	v_mul_f32_e32 v177, v177, v181
	v_mul_f32_e32 v178, v178, v182
	v_mul_f32_e32 v179, v179, v183
	v_add_f32_e32 v176, v176, v76
	v_add_f32_e32 v177, v177, v77
	v_add_f32_e32 v178, v178, v78
	v_add_f32_e32 v179, v179, v79
	v_add_f32_e32 v176, v176, v84
	v_add_f32_e32 v177, v177, v85
	v_add_f32_e32 v178, v178, v86
	v_add_f32_e32 v179, v179, v87
	v_add_f32_e32 v176, v176, v88
	v_add_f32_e32 v177, v177, v89
	v_add_f32_e32 v178, v178, v90
	v_add_f32_e32 v179, v179, v91
	v_add_f32_e32 v176, v176, v96
	v_add_f32_e32 v177, v177, v97
	v_add_f32_e32 v178, v178, v98
	v_add_f32_e32 v179, v179, v99
	v_cvt_pk_bf16_f32 v80, v76, v76
	ds_write_b16 v188, v80 offset:0
	v_cvt_pk_bf16_f32 v81, v77, v77
	ds_write_b16 v188, v81 offset:160
	v_cvt_pk_bf16_f32 v124, v78, v78
	ds_write_b16 v188, v124 offset:320
	v_cvt_pk_bf16_f32 v126, v79, v79
	ds_write_b16 v188, v126 offset:480
	v_cvt_pk_bf16_f32 v80, v84, v84
	ds_write_b16 v188, v80 offset:32
	v_cvt_pk_bf16_f32 v81, v85, v85
	ds_write_b16 v188, v81 offset:192
	v_cvt_pk_bf16_f32 v124, v86, v86
	ds_write_b16 v188, v124 offset:352
	v_cvt_pk_bf16_f32 v126, v87, v87
	ds_write_b16 v188, v126 offset:512
	v_cvt_pk_bf16_f32 v80, v88, v88
	ds_write_b16 v188, v80 offset:64
	v_cvt_pk_bf16_f32 v81, v89, v89
	ds_write_b16 v188, v81 offset:224
	v_cvt_pk_bf16_f32 v124, v90, v90
	ds_write_b16 v188, v124 offset:384
	v_cvt_pk_bf16_f32 v126, v91, v91
	ds_write_b16 v188, v126 offset:544
	v_cvt_pk_bf16_f32 v80, v96, v96
	ds_write_b16 v188, v80 offset:96
	v_cvt_pk_bf16_f32 v81, v97, v97
	ds_write_b16 v188, v81 offset:256
	v_cvt_pk_bf16_f32 v124, v98, v98
	ds_write_b16 v188, v124 offset:416
	v_cvt_pk_bf16_f32 v126, v99, v99
	ds_write_b16 v188, v126 offset:576
	v_mul_f32_e32 v100, v100, v180
	v_mul_f32_e32 v101, v101, v181
	v_mul_f32_e32 v102, v102, v182
	v_mul_f32_e32 v103, v103, v183
	v_mul_f32_e32 v132, v132, v180
	v_mul_f32_e32 v133, v133, v181
	v_mul_f32_e32 v134, v134, v182
	v_mul_f32_e32 v135, v135, v183
	v_mul_f32_e32 v140, v140, v180
	v_mul_f32_e32 v141, v141, v181
	v_mul_f32_e32 v142, v142, v182
	v_mul_f32_e32 v143, v143, v183
	v_mul_f32_e32 v144, v144, v180
	v_mul_f32_e32 v145, v145, v181
	v_mul_f32_e32 v146, v146, v182
	v_mul_f32_e32 v147, v147, v183
	s_waitcnt lgkmcnt(0)
	ds_read_b128 v[164:167], v191 offset:0
	ds_read_b128 v[168:171], v191 offset:64
	s_waitcnt vmcnt(0)
	s_waitcnt lgkmcnt(0)
	v_mfma_f32_16x16x32_bf16 v[100:103], v[164:167], v[44:47], v[100:103]
	v_mfma_f32_16x16x32_bf16 v[132:135], v[164:167], v[48:51], v[132:135]
	v_mfma_f32_16x16x32_bf16 v[140:143], v[164:167], v[52:55], v[140:143]
	v_mfma_f32_16x16x32_bf16 v[144:147], v[164:167], v[56:59], v[144:147]
	v_mfma_f32_16x16x32_bf16 v[100:103], v[168:171], v[60:63], v[100:103]
	v_mfma_f32_16x16x32_bf16 v[132:135], v[168:171], v[64:67], v[132:135]
	v_mfma_f32_16x16x32_bf16 v[140:143], v[168:171], v[68:71], v[140:143]
	v_mfma_f32_16x16x32_bf16 v[144:147], v[168:171], v[72:75], v[144:147]
	s_nop 3
	ds_read_b128 v[44:47], v138 offset:0
	ds_read_b128 v[48:51], v138 offset:8448
	ds_read_b128 v[52:55], v138 offset:16896
	ds_read_b128 v[56:59], v138 offset:25344
	ds_read_b128 v[60:63], v138 offset:64
	ds_read_b128 v[64:67], v138 offset:8512
	ds_read_b128 v[68:71], v138 offset:16960
	ds_read_b128 v[72:75], v138 offset:25408
	s_waitcnt vmcnt(0) lgkmcnt(8)
	v_mov_b32_e32 v76, 0
	v_mov_b32_e32 v77, 0
	v_mov_b32_e32 v78, 0
	v_mov_b32_e32 v79, 0
	v_mov_b32_e32 v84, 0
	v_mov_b32_e32 v85, 0
	v_mov_b32_e32 v86, 0
	v_mov_b32_e32 v87, 0
	v_mov_b32_e32 v88, 0
	v_mov_b32_e32 v89, 0
	v_mov_b32_e32 v90, 0
	v_mov_b32_e32 v91, 0
	v_mov_b32_e32 v96, 0
	v_mov_b32_e32 v97, 0
	v_mov_b32_e32 v98, 0
	v_mov_b32_e32 v99, 0
	s_nop 1
	v_mfma_f32_16x16x32_bf16 v[76:79], v[4:7], v[12:15], v[76:79]
	v_mfma_f32_16x16x32_bf16 v[76:79], v[8:11], v[16:19], v[76:79]
	v_mfma_f32_16x16x32_bf16 v[84:87], v[4:7], v[20:23], v[84:87]
	v_mfma_f32_16x16x32_bf16 v[84:87], v[8:11], v[24:27], v[84:87]
	v_mfma_f32_16x16x32_bf16 v[88:91], v[4:7], v[28:31], v[88:91]
	v_mfma_f32_16x16x32_bf16 v[88:91], v[8:11], v[32:35], v[88:91]
	v_mfma_f32_16x16x32_bf16 v[96:99], v[4:7], v[36:39], v[96:99]
	v_mfma_f32_16x16x32_bf16 v[96:99], v[8:11], v[40:43], v[96:99]
	s_nop 3
	ds_read_b128 v[12:15], v136 offset:9216
	ds_read_b128 v[16:19], v136 offset:9280
	ds_read_b128 v[20:23], v136 offset:11520
	ds_read_b128 v[24:27], v136 offset:11584
	ds_read_b128 v[28:31], v136 offset:13824
	ds_read_b128 v[32:35], v136 offset:13888
	ds_read_b128 v[36:39], v136 offset:16128
	ds_read_b128 v[40:43], v136 offset:16192
	s_nop 7
	v_mul_f32_e32 v76, 0x3e000000, v76
	v_mul_f32_e32 v77, 0x3e000000, v77
	v_mul_f32_e32 v78, 0x3e000000, v78
	v_mul_f32_e32 v79, 0x3e000000, v79
	v_mul_f32_e32 v84, 0x3e000000, v84
	v_mul_f32_e32 v85, 0x3e000000, v85
	v_mul_f32_e32 v86, 0x3e000000, v86
	v_mul_f32_e32 v87, 0x3e000000, v87
	v_mul_f32_e32 v88, 0x3e000000, v88
	v_mul_f32_e32 v89, 0x3e000000, v89
	v_mul_f32_e32 v90, 0x3e000000, v90
	v_mul_f32_e32 v91, 0x3e000000, v91
	v_mul_f32_e32 v96, 0x3e000000, v96
	v_mul_f32_e32 v97, 0x3e000000, v97
	v_mul_f32_e32 v98, 0x3e000000, v98
	v_mul_f32_e32 v99, 0x3e000000, v99
	v_max3_f32 v184, v76, v84, v88
	v_max_f32_e32 v184, v184, v96
	v_max3_f32 v185, v77, v85, v89
	v_max_f32_e32 v185, v185, v97
	v_max3_f32 v186, v78, v86, v90
	v_max_f32_e32 v186, v186, v98
	v_max3_f32 v187, v79, v87, v91
	v_max_f32_e32 v187, v187, v99
	s_nop 0
	v_max_f32_dpp v184, v184, v184 quad_perm:[1,0,3,2] row_mask:0xf bank_mask:0xf
	v_max_f32_dpp v185, v185, v185 quad_perm:[1,0,3,2] row_mask:0xf bank_mask:0xf
	v_max_f32_dpp v186, v186, v186 quad_perm:[1,0,3,2] row_mask:0xf bank_mask:0xf
	v_max_f32_dpp v187, v187, v187 quad_perm:[1,0,3,2] row_mask:0xf bank_mask:0xf
	v_max_f32_dpp v184, v184, v184 quad_perm:[2,3,0,1] row_mask:0xf bank_mask:0xf
	v_max_f32_dpp v185, v185, v185 quad_perm:[2,3,0,1] row_mask:0xf bank_mask:0xf
	v_max_f32_dpp v186, v186, v186 quad_perm:[2,3,0,1] row_mask:0xf bank_mask:0xf
	v_max_f32_dpp v187, v187, v187 quad_perm:[2,3,0,1] row_mask:0xf bank_mask:0xf
	v_max_f32_dpp v184, v184, v184 row_half_mirror row_mask:0xf bank_mask:0xf
	v_max_f32_dpp v185, v185, v185 row_half_mirror row_mask:0xf bank_mask:0xf
	v_max_f32_dpp v186, v186, v186 row_half_mirror row_mask:0xf bank_mask:0xf
	v_max_f32_dpp v187, v187, v187 row_half_mirror row_mask:0xf bank_mask:0xf
	v_max_f32_dpp v184, v184, v184 row_ror:8 row_mask:0xf bank_mask:0xf
	v_max_f32_dpp v185, v185, v185 row_ror:8 row_mask:0xf bank_mask:0xf
	v_max_f32_dpp v186, v186, v186 row_ror:8 row_mask:0xf bank_mask:0xf
	v_max_f32_dpp v187, v187, v187 row_ror:8 row_mask:0xf bank_mask:0xf
	v_max_f32_e32 v184, v172, v184
	v_max_f32_e32 v185, v173, v185
	v_max_f32_e32 v186, v174, v186
	v_max_f32_e32 v187, v175, v187
	v_sub_f32_e32 v180, v172, v184
	v_mov_b32_e32 v172, v184
	v_sub_f32_e32 v181, v173, v185
	v_mov_b32_e32 v173, v185
	v_sub_f32_e32 v182, v174, v186
	v_mov_b32_e32 v174, v186
	v_sub_f32_e32 v183, v175, v187
	v_mov_b32_e32 v175, v187
	v_mul_f32_e32 v180, 0x3fb8aa3b, v180
	v_mul_f32_e32 v181, 0x3fb8aa3b, v181
	v_mul_f32_e32 v182, 0x3fb8aa3b, v182
	v_mul_f32_e32 v183, 0x3fb8aa3b, v183
	v_exp_f32_e32 v180, v180
	v_exp_f32_e32 v181, v181
	v_exp_f32_e32 v182, v182
	v_exp_f32_e32 v183, v183
	v_sub_f32_e32 v76, v76, v172
	v_sub_f32_e32 v77, v77, v173
	v_sub_f32_e32 v78, v78, v174
	v_sub_f32_e32 v79, v79, v175
	v_sub_f32_e32 v84, v84, v172
	v_sub_f32_e32 v85, v85, v173
	v_sub_f32_e32 v86, v86, v174
	v_sub_f32_e32 v87, v87, v175
	v_sub_f32_e32 v88, v88, v172
	v_sub_f32_e32 v89, v89, v173
	v_sub_f32_e32 v90, v90, v174
	v_sub_f32_e32 v91, v91, v175
	v_sub_f32_e32 v96, v96, v172
	v_sub_f32_e32 v97, v97, v173
	v_sub_f32_e32 v98, v98, v174
	v_sub_f32_e32 v99, v99, v175
	v_mul_f32_e32 v76, 0x3fb8aa3b, v76
	v_mul_f32_e32 v77, 0x3fb8aa3b, v77
	v_mul_f32_e32 v78, 0x3fb8aa3b, v78
	v_mul_f32_e32 v79, 0x3fb8aa3b, v79
	v_mul_f32_e32 v84, 0x3fb8aa3b, v84
	v_mul_f32_e32 v85, 0x3fb8aa3b, v85
	v_mul_f32_e32 v86, 0x3fb8aa3b, v86
	v_mul_f32_e32 v87, 0x3fb8aa3b, v87
	v_mul_f32_e32 v88, 0x3fb8aa3b, v88
	v_mul_f32_e32 v89, 0x3fb8aa3b, v89
	v_mul_f32_e32 v90, 0x3fb8aa3b, v90
	v_mul_f32_e32 v91, 0x3fb8aa3b, v91
	v_mul_f32_e32 v96, 0x3fb8aa3b, v96
	v_mul_f32_e32 v97, 0x3fb8aa3b, v97
	v_mul_f32_e32 v98, 0x3fb8aa3b, v98
	v_mul_f32_e32 v99, 0x3fb8aa3b, v99
	v_exp_f32_e32 v76, v76
	v_exp_f32_e32 v77, v77
	v_exp_f32_e32 v78, v78
	v_exp_f32_e32 v79, v79
	v_exp_f32_e32 v84, v84
	v_exp_f32_e32 v85, v85
	v_exp_f32_e32 v86, v86
	v_exp_f32_e32 v87, v87
	v_exp_f32_e32 v88, v88
	v_exp_f32_e32 v89, v89
	v_exp_f32_e32 v90, v90
	v_exp_f32_e32 v91, v91
	v_exp_f32_e32 v96, v96
	v_exp_f32_e32 v97, v97
	v_exp_f32_e32 v98, v98
	v_exp_f32_e32 v99, v99
	s_nop 0
	v_mul_f32_e32 v176, v176, v180
	v_mul_f32_e32 v177, v177, v181
	v_mul_f32_e32 v178, v178, v182
	v_mul_f32_e32 v179, v179, v183
	v_add_f32_e32 v176, v176, v76
	v_add_f32_e32 v177, v177, v77
	v_add_f32_e32 v178, v178, v78
	v_add_f32_e32 v179, v179, v79
	v_add_f32_e32 v176, v176, v84
	v_add_f32_e32 v177, v177, v85
	v_add_f32_e32 v178, v178, v86
	v_add_f32_e32 v179, v179, v87
	v_add_f32_e32 v176, v176, v88
	v_add_f32_e32 v177, v177, v89
	v_add_f32_e32 v178, v178, v90
	v_add_f32_e32 v179, v179, v91
	v_add_f32_e32 v176, v176, v96
	v_add_f32_e32 v177, v177, v97
	v_add_f32_e32 v178, v178, v98
	v_add_f32_e32 v179, v179, v99
	v_cvt_pk_bf16_f32 v80, v76, v76
	ds_write_b16 v188, v80 offset:0
	v_cvt_pk_bf16_f32 v81, v77, v77
	ds_write_b16 v188, v81 offset:160
	v_cvt_pk_bf16_f32 v124, v78, v78
	ds_write_b16 v188, v124 offset:320
	v_cvt_pk_bf16_f32 v126, v79, v79
	ds_write_b16 v188, v126 offset:480
	v_cvt_pk_bf16_f32 v80, v84, v84
	ds_write_b16 v188, v80 offset:32
	v_cvt_pk_bf16_f32 v81, v85, v85
	ds_write_b16 v188, v81 offset:192
	v_cvt_pk_bf16_f32 v124, v86, v86
	ds_write_b16 v188, v124 offset:352
	v_cvt_pk_bf16_f32 v126, v87, v87
	ds_write_b16 v188, v126 offset:512
	v_cvt_pk_bf16_f32 v80, v88, v88
	ds_write_b16 v188, v80 offset:64
	v_cvt_pk_bf16_f32 v81, v89, v89
	ds_write_b16 v188, v81 offset:224
	v_cvt_pk_bf16_f32 v124, v90, v90
	ds_write_b16 v188, v124 offset:384
	v_cvt_pk_bf16_f32 v126, v91, v91
	ds_write_b16 v188, v126 offset:544
	v_cvt_pk_bf16_f32 v80, v96, v96
	ds_write_b16 v188, v80 offset:96
	v_cvt_pk_bf16_f32 v81, v97, v97
	ds_write_b16 v188, v81 offset:256
	v_cvt_pk_bf16_f32 v124, v98, v98
	ds_write_b16 v188, v124 offset:416
	v_cvt_pk_bf16_f32 v126, v99, v99
	ds_write_b16 v188, v126 offset:576
	v_mul_f32_e32 v100, v100, v180
	v_mul_f32_e32 v101, v101, v181
	v_mul_f32_e32 v102, v102, v182
	v_mul_f32_e32 v103, v103, v183
	v_mul_f32_e32 v132, v132, v180
	v_mul_f32_e32 v133, v133, v181
	v_mul_f32_e32 v134, v134, v182
	v_mul_f32_e32 v135, v135, v183
	v_mul_f32_e32 v140, v140, v180
	v_mul_f32_e32 v141, v141, v181
	v_mul_f32_e32 v142, v142, v182
	v_mul_f32_e32 v143, v143, v183
	v_mul_f32_e32 v144, v144, v180
	v_mul_f32_e32 v145, v145, v181
	v_mul_f32_e32 v146, v146, v182
	v_mul_f32_e32 v147, v147, v183
	s_waitcnt lgkmcnt(0)
	ds_read_b128 v[164:167], v191 offset:0
	ds_read_b128 v[168:171], v191 offset:64
	s_waitcnt lgkmcnt(0)
	v_mfma_f32_16x16x32_bf16 v[100:103], v[164:167], v[44:47], v[100:103]
	v_mfma_f32_16x16x32_bf16 v[132:135], v[164:167], v[48:51], v[132:135]
	v_mfma_f32_16x16x32_bf16 v[140:143], v[164:167], v[52:55], v[140:143]
	v_mfma_f32_16x16x32_bf16 v[144:147], v[164:167], v[56:59], v[144:147]
	v_mfma_f32_16x16x32_bf16 v[100:103], v[168:171], v[60:63], v[100:103]
	v_mfma_f32_16x16x32_bf16 v[132:135], v[168:171], v[64:67], v[132:135]
	v_mfma_f32_16x16x32_bf16 v[140:143], v[168:171], v[68:71], v[140:143]
	v_mfma_f32_16x16x32_bf16 v[144:147], v[168:171], v[72:75], v[144:147]
	s_nop 3
	ds_read_b128 v[44:47], v138 offset:128
	ds_read_b128 v[48:51], v138 offset:8576
	ds_read_b128 v[52:55], v138 offset:17024
	ds_read_b128 v[56:59], v138 offset:25472
	ds_read_b128 v[60:63], v138 offset:192
	ds_read_b128 v[64:67], v138 offset:8640
	ds_read_b128 v[68:71], v138 offset:17088
	ds_read_b128 v[72:75], v138 offset:25536
	s_waitcnt lgkmcnt(8)
	v_mov_b32_e32 v76, 0
	v_mov_b32_e32 v77, 0
	v_mov_b32_e32 v78, 0
	v_mov_b32_e32 v79, 0
	v_mov_b32_e32 v84, 0
	v_mov_b32_e32 v85, 0
	v_mov_b32_e32 v86, 0
	v_mov_b32_e32 v87, 0
	v_mov_b32_e32 v88, 0
	v_mov_b32_e32 v89, 0
	v_mov_b32_e32 v90, 0
	v_mov_b32_e32 v91, 0
	v_mov_b32_e32 v96, 0
	v_mov_b32_e32 v97, 0
	v_mov_b32_e32 v98, 0
	v_mov_b32_e32 v99, 0
	s_nop 1
	v_mfma_f32_16x16x32_bf16 v[76:79], v[4:7], v[12:15], v[76:79]
	v_mfma_f32_16x16x32_bf16 v[76:79], v[8:11], v[16:19], v[76:79]
	v_mfma_f32_16x16x32_bf16 v[84:87], v[4:7], v[20:23], v[84:87]
	v_mfma_f32_16x16x32_bf16 v[84:87], v[8:11], v[24:27], v[84:87]
	v_mfma_f32_16x16x32_bf16 v[88:91], v[4:7], v[28:31], v[88:91]
	v_mfma_f32_16x16x32_bf16 v[88:91], v[8:11], v[32:35], v[88:91]
	v_mfma_f32_16x16x32_bf16 v[96:99], v[4:7], v[36:39], v[96:99]
	v_mfma_f32_16x16x32_bf16 v[96:99], v[8:11], v[40:43], v[96:99]
	s_nop 3
	ds_read_b128 v[12:15], v136 offset:18432
	ds_read_b128 v[16:19], v136 offset:18496
	ds_read_b128 v[20:23], v136 offset:20736
	ds_read_b128 v[24:27], v136 offset:20800
	ds_read_b128 v[28:31], v136 offset:23040
	ds_read_b128 v[32:35], v136 offset:23104
	ds_read_b128 v[36:39], v136 offset:25344
	ds_read_b128 v[40:43], v136 offset:25408
	s_nop 7
	v_mul_f32_e32 v76, 0x3e000000, v76
	v_mul_f32_e32 v77, 0x3e000000, v77
	v_mul_f32_e32 v78, 0x3e000000, v78
	v_mul_f32_e32 v79, 0x3e000000, v79
	v_mul_f32_e32 v84, 0x3e000000, v84
	v_mul_f32_e32 v85, 0x3e000000, v85
	v_mul_f32_e32 v86, 0x3e000000, v86
	v_mul_f32_e32 v87, 0x3e000000, v87
	v_mul_f32_e32 v88, 0x3e000000, v88
	v_mul_f32_e32 v89, 0x3e000000, v89
	v_mul_f32_e32 v90, 0x3e000000, v90
	v_mul_f32_e32 v91, 0x3e000000, v91
	v_mul_f32_e32 v96, 0x3e000000, v96
	v_mul_f32_e32 v97, 0x3e000000, v97
	v_mul_f32_e32 v98, 0x3e000000, v98
	v_mul_f32_e32 v99, 0x3e000000, v99
	v_max3_f32 v184, v76, v84, v88
	v_max_f32_e32 v184, v184, v96
	v_max3_f32 v185, v77, v85, v89
	v_max_f32_e32 v185, v185, v97
	v_max3_f32 v186, v78, v86, v90
	v_max_f32_e32 v186, v186, v98
	v_max3_f32 v187, v79, v87, v91
	v_max_f32_e32 v187, v187, v99
	s_nop 0
	v_max_f32_dpp v184, v184, v184 quad_perm:[1,0,3,2] row_mask:0xf bank_mask:0xf
	v_max_f32_dpp v185, v185, v185 quad_perm:[1,0,3,2] row_mask:0xf bank_mask:0xf
	v_max_f32_dpp v186, v186, v186 quad_perm:[1,0,3,2] row_mask:0xf bank_mask:0xf
	v_max_f32_dpp v187, v187, v187 quad_perm:[1,0,3,2] row_mask:0xf bank_mask:0xf
	v_max_f32_dpp v184, v184, v184 quad_perm:[2,3,0,1] row_mask:0xf bank_mask:0xf
	v_max_f32_dpp v185, v185, v185 quad_perm:[2,3,0,1] row_mask:0xf bank_mask:0xf
	v_max_f32_dpp v186, v186, v186 quad_perm:[2,3,0,1] row_mask:0xf bank_mask:0xf
	v_max_f32_dpp v187, v187, v187 quad_perm:[2,3,0,1] row_mask:0xf bank_mask:0xf
	v_max_f32_dpp v184, v184, v184 row_half_mirror row_mask:0xf bank_mask:0xf
	v_max_f32_dpp v185, v185, v185 row_half_mirror row_mask:0xf bank_mask:0xf
	v_max_f32_dpp v186, v186, v186 row_half_mirror row_mask:0xf bank_mask:0xf
	v_max_f32_dpp v187, v187, v187 row_half_mirror row_mask:0xf bank_mask:0xf
	v_max_f32_dpp v184, v184, v184 row_ror:8 row_mask:0xf bank_mask:0xf
	v_max_f32_dpp v185, v185, v185 row_ror:8 row_mask:0xf bank_mask:0xf
	v_max_f32_dpp v186, v186, v186 row_ror:8 row_mask:0xf bank_mask:0xf
	v_max_f32_dpp v187, v187, v187 row_ror:8 row_mask:0xf bank_mask:0xf
	v_max_f32_e32 v184, v172, v184
	v_max_f32_e32 v185, v173, v185
	v_max_f32_e32 v186, v174, v186
	v_max_f32_e32 v187, v175, v187
	v_sub_f32_e32 v180, v172, v184
	v_mov_b32_e32 v172, v184
	v_sub_f32_e32 v181, v173, v185
	v_mov_b32_e32 v173, v185
	v_sub_f32_e32 v182, v174, v186
	v_mov_b32_e32 v174, v186
	v_sub_f32_e32 v183, v175, v187
	v_mov_b32_e32 v175, v187
	v_mul_f32_e32 v180, 0x3fb8aa3b, v180
	v_mul_f32_e32 v181, 0x3fb8aa3b, v181
	v_mul_f32_e32 v182, 0x3fb8aa3b, v182
	v_mul_f32_e32 v183, 0x3fb8aa3b, v183
	v_exp_f32_e32 v180, v180
	v_exp_f32_e32 v181, v181
	v_exp_f32_e32 v182, v182
	v_exp_f32_e32 v183, v183
	v_sub_f32_e32 v76, v76, v172
	v_sub_f32_e32 v77, v77, v173
	v_sub_f32_e32 v78, v78, v174
	v_sub_f32_e32 v79, v79, v175
	v_sub_f32_e32 v84, v84, v172
	v_sub_f32_e32 v85, v85, v173
	v_sub_f32_e32 v86, v86, v174
	v_sub_f32_e32 v87, v87, v175
	v_sub_f32_e32 v88, v88, v172
	v_sub_f32_e32 v89, v89, v173
	v_sub_f32_e32 v90, v90, v174
	v_sub_f32_e32 v91, v91, v175
	v_sub_f32_e32 v96, v96, v172
	v_sub_f32_e32 v97, v97, v173
	v_sub_f32_e32 v98, v98, v174
	v_sub_f32_e32 v99, v99, v175
	v_mul_f32_e32 v76, 0x3fb8aa3b, v76
	v_mul_f32_e32 v77, 0x3fb8aa3b, v77
	v_mul_f32_e32 v78, 0x3fb8aa3b, v78
	v_mul_f32_e32 v79, 0x3fb8aa3b, v79
	v_mul_f32_e32 v84, 0x3fb8aa3b, v84
	v_mul_f32_e32 v85, 0x3fb8aa3b, v85
	v_mul_f32_e32 v86, 0x3fb8aa3b, v86
	v_mul_f32_e32 v87, 0x3fb8aa3b, v87
	v_mul_f32_e32 v88, 0x3fb8aa3b, v88
	v_mul_f32_e32 v89, 0x3fb8aa3b, v89
	v_mul_f32_e32 v90, 0x3fb8aa3b, v90
	v_mul_f32_e32 v91, 0x3fb8aa3b, v91
	v_mul_f32_e32 v96, 0x3fb8aa3b, v96
	v_mul_f32_e32 v97, 0x3fb8aa3b, v97
	v_mul_f32_e32 v98, 0x3fb8aa3b, v98
	v_mul_f32_e32 v99, 0x3fb8aa3b, v99
	v_exp_f32_e32 v76, v76
	v_exp_f32_e32 v77, v77
	v_exp_f32_e32 v78, v78
	v_exp_f32_e32 v79, v79
	v_exp_f32_e32 v84, v84
	v_exp_f32_e32 v85, v85
	v_exp_f32_e32 v86, v86
	v_exp_f32_e32 v87, v87
	v_exp_f32_e32 v88, v88
	v_exp_f32_e32 v89, v89
	v_exp_f32_e32 v90, v90
	v_exp_f32_e32 v91, v91
	v_exp_f32_e32 v96, v96
	v_exp_f32_e32 v97, v97
	v_exp_f32_e32 v98, v98
	v_exp_f32_e32 v99, v99
	s_nop 0
	v_mul_f32_e32 v176, v176, v180
	v_mul_f32_e32 v177, v177, v181
	v_mul_f32_e32 v178, v178, v182
	v_mul_f32_e32 v179, v179, v183
	v_add_f32_e32 v176, v176, v76
	v_add_f32_e32 v177, v177, v77
	v_add_f32_e32 v178, v178, v78
	v_add_f32_e32 v179, v179, v79
	v_add_f32_e32 v176, v176, v84
	v_add_f32_e32 v177, v177, v85
	v_add_f32_e32 v178, v178, v86
	v_add_f32_e32 v179, v179, v87
	v_add_f32_e32 v176, v176, v88
	v_add_f32_e32 v177, v177, v89
	v_add_f32_e32 v178, v178, v90
	v_add_f32_e32 v179, v179, v91
	v_add_f32_e32 v176, v176, v96
	v_add_f32_e32 v177, v177, v97
	v_add_f32_e32 v178, v178, v98
	v_add_f32_e32 v179, v179, v99
	v_cvt_pk_bf16_f32 v80, v76, v76
	ds_write_b16 v188, v80 offset:0
	v_cvt_pk_bf16_f32 v81, v77, v77
	ds_write_b16 v188, v81 offset:160
	v_cvt_pk_bf16_f32 v124, v78, v78
	ds_write_b16 v188, v124 offset:320
	v_cvt_pk_bf16_f32 v126, v79, v79
	ds_write_b16 v188, v126 offset:480
	v_cvt_pk_bf16_f32 v80, v84, v84
	ds_write_b16 v188, v80 offset:32
	v_cvt_pk_bf16_f32 v81, v85, v85
	ds_write_b16 v188, v81 offset:192
	v_cvt_pk_bf16_f32 v124, v86, v86
	ds_write_b16 v188, v124 offset:352
	v_cvt_pk_bf16_f32 v126, v87, v87
	ds_write_b16 v188, v126 offset:512
	v_cvt_pk_bf16_f32 v80, v88, v88
	ds_write_b16 v188, v80 offset:64
	v_cvt_pk_bf16_f32 v81, v89, v89
	ds_write_b16 v188, v81 offset:224
	v_cvt_pk_bf16_f32 v124, v90, v90
	ds_write_b16 v188, v124 offset:384
	v_cvt_pk_bf16_f32 v126, v91, v91
	ds_write_b16 v188, v126 offset:544
	v_cvt_pk_bf16_f32 v80, v96, v96
	ds_write_b16 v188, v80 offset:96
	v_cvt_pk_bf16_f32 v81, v97, v97
	ds_write_b16 v188, v81 offset:256
	v_cvt_pk_bf16_f32 v124, v98, v98
	ds_write_b16 v188, v124 offset:416
	v_cvt_pk_bf16_f32 v126, v99, v99
	ds_write_b16 v188, v126 offset:576
	v_mul_f32_e32 v100, v100, v180
	v_mul_f32_e32 v101, v101, v181
	v_mul_f32_e32 v102, v102, v182
	v_mul_f32_e32 v103, v103, v183
	v_mul_f32_e32 v132, v132, v180
	v_mul_f32_e32 v133, v133, v181
	v_mul_f32_e32 v134, v134, v182
	v_mul_f32_e32 v135, v135, v183
	v_mul_f32_e32 v140, v140, v180
	v_mul_f32_e32 v141, v141, v181
	v_mul_f32_e32 v142, v142, v182
	v_mul_f32_e32 v143, v143, v183
	v_mul_f32_e32 v144, v144, v180
	v_mul_f32_e32 v145, v145, v181
	v_mul_f32_e32 v146, v146, v182
	v_mul_f32_e32 v147, v147, v183
	s_waitcnt lgkmcnt(0)
	ds_read_b128 v[164:167], v191 offset:0
	ds_read_b128 v[168:171], v191 offset:64
	s_waitcnt lgkmcnt(0)
	v_mfma_f32_16x16x32_bf16 v[100:103], v[164:167], v[44:47], v[100:103]
	v_mfma_f32_16x16x32_bf16 v[132:135], v[164:167], v[48:51], v[132:135]
	v_mfma_f32_16x16x32_bf16 v[140:143], v[164:167], v[52:55], v[140:143]
	v_mfma_f32_16x16x32_bf16 v[144:147], v[164:167], v[56:59], v[144:147]
	v_mfma_f32_16x16x32_bf16 v[100:103], v[168:171], v[60:63], v[100:103]
	v_mfma_f32_16x16x32_bf16 v[132:135], v[168:171], v[64:67], v[132:135]
	v_mfma_f32_16x16x32_bf16 v[140:143], v[168:171], v[68:71], v[140:143]
	v_mfma_f32_16x16x32_bf16 v[144:147], v[168:171], v[72:75], v[144:147]
	s_nop 3
	ds_read_b128 v[44:47], v138 offset:256
	ds_read_b128 v[48:51], v138 offset:8704
	ds_read_b128 v[52:55], v138 offset:17152
	ds_read_b128 v[56:59], v138 offset:25600
	ds_read_b128 v[60:63], v138 offset:320
	ds_read_b128 v[64:67], v138 offset:8768
	ds_read_b128 v[68:71], v138 offset:17216
	ds_read_b128 v[72:75], v138 offset:25664
	s_waitcnt lgkmcnt(8)
	v_mov_b32_e32 v76, 0
	v_mov_b32_e32 v77, 0
	v_mov_b32_e32 v78, 0
	v_mov_b32_e32 v79, 0
	v_mov_b32_e32 v84, 0
	v_mov_b32_e32 v85, 0
	v_mov_b32_e32 v86, 0
	v_mov_b32_e32 v87, 0
	v_mov_b32_e32 v88, 0
	v_mov_b32_e32 v89, 0
	v_mov_b32_e32 v90, 0
	v_mov_b32_e32 v91, 0
	v_mov_b32_e32 v96, 0
	v_mov_b32_e32 v97, 0
	v_mov_b32_e32 v98, 0
	v_mov_b32_e32 v99, 0
	s_nop 1
	v_mfma_f32_16x16x32_bf16 v[76:79], v[4:7], v[12:15], v[76:79]
	v_mfma_f32_16x16x32_bf16 v[76:79], v[8:11], v[16:19], v[76:79]
	v_mfma_f32_16x16x32_bf16 v[84:87], v[4:7], v[20:23], v[84:87]
	v_mfma_f32_16x16x32_bf16 v[84:87], v[8:11], v[24:27], v[84:87]
	v_mfma_f32_16x16x32_bf16 v[88:91], v[4:7], v[28:31], v[88:91]
	v_mfma_f32_16x16x32_bf16 v[88:91], v[8:11], v[32:35], v[88:91]
	v_mfma_f32_16x16x32_bf16 v[96:99], v[4:7], v[36:39], v[96:99]
	v_mfma_f32_16x16x32_bf16 v[96:99], v[8:11], v[40:43], v[96:99]
	s_nop 3
	ds_read_b128 v[12:15], v136 offset:27648
	ds_read_b128 v[16:19], v136 offset:27712
	ds_read_b128 v[20:23], v136 offset:29952
	ds_read_b128 v[24:27], v136 offset:30016
	ds_read_b128 v[28:31], v136 offset:32256
	ds_read_b128 v[32:35], v136 offset:32320
	ds_read_b128 v[36:39], v136 offset:34560
	ds_read_b128 v[40:43], v136 offset:34624
	s_nop 7
	v_mul_f32_e32 v76, 0x3e000000, v76
	v_mul_f32_e32 v77, 0x3e000000, v77
	v_mul_f32_e32 v78, 0x3e000000, v78
	v_mul_f32_e32 v79, 0x3e000000, v79
	v_mul_f32_e32 v84, 0x3e000000, v84
	v_mul_f32_e32 v85, 0x3e000000, v85
	v_mul_f32_e32 v86, 0x3e000000, v86
	v_mul_f32_e32 v87, 0x3e000000, v87
	v_mul_f32_e32 v88, 0x3e000000, v88
	v_mul_f32_e32 v89, 0x3e000000, v89
	v_mul_f32_e32 v90, 0x3e000000, v90
	v_mul_f32_e32 v91, 0x3e000000, v91
	v_mul_f32_e32 v96, 0x3e000000, v96
	v_mul_f32_e32 v97, 0x3e000000, v97
	v_mul_f32_e32 v98, 0x3e000000, v98
	v_mul_f32_e32 v99, 0x3e000000, v99
	v_max3_f32 v184, v76, v84, v88
	v_max_f32_e32 v184, v184, v96
	v_max3_f32 v185, v77, v85, v89
	v_max_f32_e32 v185, v185, v97
	v_max3_f32 v186, v78, v86, v90
	v_max_f32_e32 v186, v186, v98
	v_max3_f32 v187, v79, v87, v91
	v_max_f32_e32 v187, v187, v99
	s_nop 0
	v_max_f32_dpp v184, v184, v184 quad_perm:[1,0,3,2] row_mask:0xf bank_mask:0xf
	v_max_f32_dpp v185, v185, v185 quad_perm:[1,0,3,2] row_mask:0xf bank_mask:0xf
	v_max_f32_dpp v186, v186, v186 quad_perm:[1,0,3,2] row_mask:0xf bank_mask:0xf
	v_max_f32_dpp v187, v187, v187 quad_perm:[1,0,3,2] row_mask:0xf bank_mask:0xf
	v_max_f32_dpp v184, v184, v184 quad_perm:[2,3,0,1] row_mask:0xf bank_mask:0xf
	v_max_f32_dpp v185, v185, v185 quad_perm:[2,3,0,1] row_mask:0xf bank_mask:0xf
	v_max_f32_dpp v186, v186, v186 quad_perm:[2,3,0,1] row_mask:0xf bank_mask:0xf
	v_max_f32_dpp v187, v187, v187 quad_perm:[2,3,0,1] row_mask:0xf bank_mask:0xf
	v_max_f32_dpp v184, v184, v184 row_half_mirror row_mask:0xf bank_mask:0xf
	v_max_f32_dpp v185, v185, v185 row_half_mirror row_mask:0xf bank_mask:0xf
	v_max_f32_dpp v186, v186, v186 row_half_mirror row_mask:0xf bank_mask:0xf
	v_max_f32_dpp v187, v187, v187 row_half_mirror row_mask:0xf bank_mask:0xf
	v_max_f32_dpp v184, v184, v184 row_ror:8 row_mask:0xf bank_mask:0xf
	v_max_f32_dpp v185, v185, v185 row_ror:8 row_mask:0xf bank_mask:0xf
	v_max_f32_dpp v186, v186, v186 row_ror:8 row_mask:0xf bank_mask:0xf
	v_max_f32_dpp v187, v187, v187 row_ror:8 row_mask:0xf bank_mask:0xf
	v_max_f32_e32 v184, v172, v184
	v_max_f32_e32 v185, v173, v185
	v_max_f32_e32 v186, v174, v186
	v_max_f32_e32 v187, v175, v187
	v_sub_f32_e32 v180, v172, v184
	v_mov_b32_e32 v172, v184
	v_sub_f32_e32 v181, v173, v185
	v_mov_b32_e32 v173, v185
	v_sub_f32_e32 v182, v174, v186
	v_mov_b32_e32 v174, v186
	v_sub_f32_e32 v183, v175, v187
	v_mov_b32_e32 v175, v187
	v_mul_f32_e32 v180, 0x3fb8aa3b, v180
	v_mul_f32_e32 v181, 0x3fb8aa3b, v181
	v_mul_f32_e32 v182, 0x3fb8aa3b, v182
	v_mul_f32_e32 v183, 0x3fb8aa3b, v183
	v_exp_f32_e32 v180, v180
	v_exp_f32_e32 v181, v181
	v_exp_f32_e32 v182, v182
	v_exp_f32_e32 v183, v183
	v_sub_f32_e32 v76, v76, v172
	v_sub_f32_e32 v77, v77, v173
	v_sub_f32_e32 v78, v78, v174
	v_sub_f32_e32 v79, v79, v175
	v_sub_f32_e32 v84, v84, v172
	v_sub_f32_e32 v85, v85, v173
	v_sub_f32_e32 v86, v86, v174
	v_sub_f32_e32 v87, v87, v175
	v_sub_f32_e32 v88, v88, v172
	v_sub_f32_e32 v89, v89, v173
	v_sub_f32_e32 v90, v90, v174
	v_sub_f32_e32 v91, v91, v175
	v_sub_f32_e32 v96, v96, v172
	v_sub_f32_e32 v97, v97, v173
	v_sub_f32_e32 v98, v98, v174
	v_sub_f32_e32 v99, v99, v175
	v_mul_f32_e32 v76, 0x3fb8aa3b, v76
	v_mul_f32_e32 v77, 0x3fb8aa3b, v77
	v_mul_f32_e32 v78, 0x3fb8aa3b, v78
	v_mul_f32_e32 v79, 0x3fb8aa3b, v79
	v_mul_f32_e32 v84, 0x3fb8aa3b, v84
	v_mul_f32_e32 v85, 0x3fb8aa3b, v85
	v_mul_f32_e32 v86, 0x3fb8aa3b, v86
	v_mul_f32_e32 v87, 0x3fb8aa3b, v87
	v_mul_f32_e32 v88, 0x3fb8aa3b, v88
	v_mul_f32_e32 v89, 0x3fb8aa3b, v89
	v_mul_f32_e32 v90, 0x3fb8aa3b, v90
	v_mul_f32_e32 v91, 0x3fb8aa3b, v91
	v_mul_f32_e32 v96, 0x3fb8aa3b, v96
	v_mul_f32_e32 v97, 0x3fb8aa3b, v97
	v_mul_f32_e32 v98, 0x3fb8aa3b, v98
	v_mul_f32_e32 v99, 0x3fb8aa3b, v99
	v_exp_f32_e32 v76, v76
	v_exp_f32_e32 v77, v77
	v_exp_f32_e32 v78, v78
	v_exp_f32_e32 v79, v79
	v_exp_f32_e32 v84, v84
	v_exp_f32_e32 v85, v85
	v_exp_f32_e32 v86, v86
	v_exp_f32_e32 v87, v87
	v_exp_f32_e32 v88, v88
	v_exp_f32_e32 v89, v89
	v_exp_f32_e32 v90, v90
	v_exp_f32_e32 v91, v91
	v_exp_f32_e32 v96, v96
	v_exp_f32_e32 v97, v97
	v_exp_f32_e32 v98, v98
	v_exp_f32_e32 v99, v99
	s_nop 0
	v_mul_f32_e32 v176, v176, v180
	v_mul_f32_e32 v177, v177, v181
	v_mul_f32_e32 v178, v178, v182
	v_mul_f32_e32 v179, v179, v183
	v_add_f32_e32 v176, v176, v76
	v_add_f32_e32 v177, v177, v77
	v_add_f32_e32 v178, v178, v78
	v_add_f32_e32 v179, v179, v79
	v_add_f32_e32 v176, v176, v84
	v_add_f32_e32 v177, v177, v85
	v_add_f32_e32 v178, v178, v86
	v_add_f32_e32 v179, v179, v87
	v_add_f32_e32 v176, v176, v88
	v_add_f32_e32 v177, v177, v89
	v_add_f32_e32 v178, v178, v90
	v_add_f32_e32 v179, v179, v91
	v_add_f32_e32 v176, v176, v96
	v_add_f32_e32 v177, v177, v97
	v_add_f32_e32 v178, v178, v98
	v_add_f32_e32 v179, v179, v99
	v_cvt_pk_bf16_f32 v80, v76, v76
	ds_write_b16 v188, v80 offset:0
	v_cvt_pk_bf16_f32 v81, v77, v77
	ds_write_b16 v188, v81 offset:160
	v_cvt_pk_bf16_f32 v124, v78, v78
	ds_write_b16 v188, v124 offset:320
	v_cvt_pk_bf16_f32 v126, v79, v79
	ds_write_b16 v188, v126 offset:480
	v_cvt_pk_bf16_f32 v80, v84, v84
	ds_write_b16 v188, v80 offset:32
	v_cvt_pk_bf16_f32 v81, v85, v85
	ds_write_b16 v188, v81 offset:192
	v_cvt_pk_bf16_f32 v124, v86, v86
	ds_write_b16 v188, v124 offset:352
	v_cvt_pk_bf16_f32 v126, v87, v87
	ds_write_b16 v188, v126 offset:512
	v_cvt_pk_bf16_f32 v80, v88, v88
	ds_write_b16 v188, v80 offset:64
	v_cvt_pk_bf16_f32 v81, v89, v89
	ds_write_b16 v188, v81 offset:224
	v_cvt_pk_bf16_f32 v124, v90, v90
	ds_write_b16 v188, v124 offset:384
	v_cvt_pk_bf16_f32 v126, v91, v91
	ds_write_b16 v188, v126 offset:544
	v_cvt_pk_bf16_f32 v80, v96, v96
	ds_write_b16 v188, v80 offset:96
	v_cvt_pk_bf16_f32 v81, v97, v97
	ds_write_b16 v188, v81 offset:256
	v_cvt_pk_bf16_f32 v124, v98, v98
	ds_write_b16 v188, v124 offset:416
	v_cvt_pk_bf16_f32 v126, v99, v99
	ds_write_b16 v188, v126 offset:576
	v_mul_f32_e32 v100, v100, v180
	v_mul_f32_e32 v101, v101, v181
	v_mul_f32_e32 v102, v102, v182
	v_mul_f32_e32 v103, v103, v183
	v_mul_f32_e32 v132, v132, v180
	v_mul_f32_e32 v133, v133, v181
	v_mul_f32_e32 v134, v134, v182
	v_mul_f32_e32 v135, v135, v183
	v_mul_f32_e32 v140, v140, v180
	v_mul_f32_e32 v141, v141, v181
	v_mul_f32_e32 v142, v142, v182
	v_mul_f32_e32 v143, v143, v183
	v_mul_f32_e32 v144, v144, v180
	v_mul_f32_e32 v145, v145, v181
	v_mul_f32_e32 v146, v146, v182
	v_mul_f32_e32 v147, v147, v183
	s_waitcnt lgkmcnt(0)
	ds_read_b128 v[164:167], v191 offset:0
	ds_read_b128 v[168:171], v191 offset:64
	s_waitcnt lgkmcnt(0)
	v_mfma_f32_16x16x32_bf16 v[100:103], v[164:167], v[44:47], v[100:103]
	v_mfma_f32_16x16x32_bf16 v[132:135], v[164:167], v[48:51], v[132:135]
	v_mfma_f32_16x16x32_bf16 v[140:143], v[164:167], v[52:55], v[140:143]
	v_mfma_f32_16x16x32_bf16 v[144:147], v[164:167], v[56:59], v[144:147]
	v_mfma_f32_16x16x32_bf16 v[100:103], v[168:171], v[60:63], v[100:103]
	v_mfma_f32_16x16x32_bf16 v[132:135], v[168:171], v[64:67], v[132:135]
	v_mfma_f32_16x16x32_bf16 v[140:143], v[168:171], v[68:71], v[140:143]
	v_mfma_f32_16x16x32_bf16 v[144:147], v[168:171], v[72:75], v[144:147]
	s_nop 3
	ds_read_b128 v[44:47], v138 offset:384
	ds_read_b128 v[48:51], v138 offset:8832
	ds_read_b128 v[52:55], v138 offset:17280
	ds_read_b128 v[56:59], v138 offset:25728
	ds_read_b128 v[60:63], v138 offset:448
	ds_read_b128 v[64:67], v138 offset:8896
	ds_read_b128 v[68:71], v138 offset:17344
	ds_read_b128 v[72:75], v138 offset:25792
	s_waitcnt lgkmcnt(8)
	v_mov_b32_e32 v76, 0
	v_mov_b32_e32 v77, 0
	v_mov_b32_e32 v78, 0
	v_mov_b32_e32 v79, 0
	v_mov_b32_e32 v84, 0
	v_mov_b32_e32 v85, 0
	v_mov_b32_e32 v86, 0
	v_mov_b32_e32 v87, 0
	v_mov_b32_e32 v88, 0
	v_mov_b32_e32 v89, 0
	v_mov_b32_e32 v90, 0
	v_mov_b32_e32 v91, 0
	v_mov_b32_e32 v96, 0
	v_mov_b32_e32 v97, 0
	v_mov_b32_e32 v98, 0
	v_mov_b32_e32 v99, 0
	s_nop 1
	v_mfma_f32_16x16x32_bf16 v[76:79], v[4:7], v[12:15], v[76:79]
	v_mfma_f32_16x16x32_bf16 v[76:79], v[8:11], v[16:19], v[76:79]
	v_mfma_f32_16x16x32_bf16 v[84:87], v[4:7], v[20:23], v[84:87]
	v_mfma_f32_16x16x32_bf16 v[84:87], v[8:11], v[24:27], v[84:87]
	v_mfma_f32_16x16x32_bf16 v[88:91], v[4:7], v[28:31], v[88:91]
	v_mfma_f32_16x16x32_bf16 v[88:91], v[8:11], v[32:35], v[88:91]
	v_mfma_f32_16x16x32_bf16 v[96:99], v[4:7], v[36:39], v[96:99]
	v_mfma_f32_16x16x32_bf16 v[96:99], v[8:11], v[40:43], v[96:99]
	s_nop 3
	s_nop 7
	v_mul_f32_e32 v76, 0x3e000000, v76
	v_mul_f32_e32 v77, 0x3e000000, v77
	v_mul_f32_e32 v78, 0x3e000000, v78
	v_mul_f32_e32 v79, 0x3e000000, v79
	v_mul_f32_e32 v84, 0x3e000000, v84
	v_mul_f32_e32 v85, 0x3e000000, v85
	v_mul_f32_e32 v86, 0x3e000000, v86
	v_mul_f32_e32 v87, 0x3e000000, v87
	v_mul_f32_e32 v88, 0x3e000000, v88
	v_mul_f32_e32 v89, 0x3e000000, v89
	v_mul_f32_e32 v90, 0x3e000000, v90
	v_mul_f32_e32 v91, 0x3e000000, v91
	v_mul_f32_e32 v96, 0x3e000000, v96
	v_mul_f32_e32 v97, 0x3e000000, v97
	v_mul_f32_e32 v98, 0x3e000000, v98
	v_mul_f32_e32 v99, 0x3e000000, v99
	v_max3_f32 v184, v76, v84, v88
	v_max_f32_e32 v184, v184, v96
	v_max3_f32 v185, v77, v85, v89
	v_max_f32_e32 v185, v185, v97
	v_max3_f32 v186, v78, v86, v90
	v_max_f32_e32 v186, v186, v98
	v_max3_f32 v187, v79, v87, v91
	v_max_f32_e32 v187, v187, v99
	s_nop 0
	v_max_f32_dpp v184, v184, v184 quad_perm:[1,0,3,2] row_mask:0xf bank_mask:0xf
	v_max_f32_dpp v185, v185, v185 quad_perm:[1,0,3,2] row_mask:0xf bank_mask:0xf
	v_max_f32_dpp v186, v186, v186 quad_perm:[1,0,3,2] row_mask:0xf bank_mask:0xf
	v_max_f32_dpp v187, v187, v187 quad_perm:[1,0,3,2] row_mask:0xf bank_mask:0xf
	v_max_f32_dpp v184, v184, v184 quad_perm:[2,3,0,1] row_mask:0xf bank_mask:0xf
	v_max_f32_dpp v185, v185, v185 quad_perm:[2,3,0,1] row_mask:0xf bank_mask:0xf
	v_max_f32_dpp v186, v186, v186 quad_perm:[2,3,0,1] row_mask:0xf bank_mask:0xf
	v_max_f32_dpp v187, v187, v187 quad_perm:[2,3,0,1] row_mask:0xf bank_mask:0xf
	v_max_f32_dpp v184, v184, v184 row_half_mirror row_mask:0xf bank_mask:0xf
	v_max_f32_dpp v185, v185, v185 row_half_mirror row_mask:0xf bank_mask:0xf
	v_max_f32_dpp v186, v186, v186 row_half_mirror row_mask:0xf bank_mask:0xf
	v_max_f32_dpp v187, v187, v187 row_half_mirror row_mask:0xf bank_mask:0xf
	v_max_f32_dpp v184, v184, v184 row_ror:8 row_mask:0xf bank_mask:0xf
	v_max_f32_dpp v185, v185, v185 row_ror:8 row_mask:0xf bank_mask:0xf
	v_max_f32_dpp v186, v186, v186 row_ror:8 row_mask:0xf bank_mask:0xf
	v_max_f32_dpp v187, v187, v187 row_ror:8 row_mask:0xf bank_mask:0xf
	v_max_f32_e32 v184, v172, v184
	v_max_f32_e32 v185, v173, v185
	v_max_f32_e32 v186, v174, v186
	v_max_f32_e32 v187, v175, v187
	v_sub_f32_e32 v180, v172, v184
	v_mov_b32_e32 v172, v184
	v_sub_f32_e32 v181, v173, v185
	v_mov_b32_e32 v173, v185
	v_sub_f32_e32 v182, v174, v186
	v_mov_b32_e32 v174, v186
	v_sub_f32_e32 v183, v175, v187
	v_mov_b32_e32 v175, v187
	v_mul_f32_e32 v180, 0x3fb8aa3b, v180
	v_mul_f32_e32 v181, 0x3fb8aa3b, v181
	v_mul_f32_e32 v182, 0x3fb8aa3b, v182
	v_mul_f32_e32 v183, 0x3fb8aa3b, v183
	v_exp_f32_e32 v180, v180
	v_exp_f32_e32 v181, v181
	v_exp_f32_e32 v182, v182
	v_exp_f32_e32 v183, v183
	v_sub_f32_e32 v76, v76, v172
	v_sub_f32_e32 v77, v77, v173
	v_sub_f32_e32 v78, v78, v174
	v_sub_f32_e32 v79, v79, v175
	v_sub_f32_e32 v84, v84, v172
	v_sub_f32_e32 v85, v85, v173
	v_sub_f32_e32 v86, v86, v174
	v_sub_f32_e32 v87, v87, v175
	v_sub_f32_e32 v88, v88, v172
	v_sub_f32_e32 v89, v89, v173
	v_sub_f32_e32 v90, v90, v174
	v_sub_f32_e32 v91, v91, v175
	v_sub_f32_e32 v96, v96, v172
	v_sub_f32_e32 v97, v97, v173
	v_sub_f32_e32 v98, v98, v174
	v_sub_f32_e32 v99, v99, v175
	v_mul_f32_e32 v76, 0x3fb8aa3b, v76
	v_mul_f32_e32 v77, 0x3fb8aa3b, v77
	v_mul_f32_e32 v78, 0x3fb8aa3b, v78
	v_mul_f32_e32 v79, 0x3fb8aa3b, v79
	v_mul_f32_e32 v84, 0x3fb8aa3b, v84
	v_mul_f32_e32 v85, 0x3fb8aa3b, v85
	v_mul_f32_e32 v86, 0x3fb8aa3b, v86
	v_mul_f32_e32 v87, 0x3fb8aa3b, v87
	v_mul_f32_e32 v88, 0x3fb8aa3b, v88
	v_mul_f32_e32 v89, 0x3fb8aa3b, v89
	v_mul_f32_e32 v90, 0x3fb8aa3b, v90
	v_mul_f32_e32 v91, 0x3fb8aa3b, v91
	v_mul_f32_e32 v96, 0x3fb8aa3b, v96
	v_mul_f32_e32 v97, 0x3fb8aa3b, v97
	v_mul_f32_e32 v98, 0x3fb8aa3b, v98
	v_mul_f32_e32 v99, 0x3fb8aa3b, v99
	v_exp_f32_e32 v76, v76
	v_exp_f32_e32 v77, v77
	v_exp_f32_e32 v78, v78
	v_exp_f32_e32 v79, v79
	v_exp_f32_e32 v84, v84
	v_exp_f32_e32 v85, v85
	v_exp_f32_e32 v86, v86
	v_exp_f32_e32 v87, v87
	v_exp_f32_e32 v88, v88
	v_exp_f32_e32 v89, v89
	v_exp_f32_e32 v90, v90
	v_exp_f32_e32 v91, v91
	v_exp_f32_e32 v96, v96
	v_exp_f32_e32 v97, v97
	v_exp_f32_e32 v98, v98
	v_exp_f32_e32 v99, v99
	s_nop 0
	v_mul_f32_e32 v176, v176, v180
	v_mul_f32_e32 v177, v177, v181
	v_mul_f32_e32 v178, v178, v182
	v_mul_f32_e32 v179, v179, v183
	v_add_f32_e32 v176, v176, v76
	v_add_f32_e32 v177, v177, v77
	v_add_f32_e32 v178, v178, v78
	v_add_f32_e32 v179, v179, v79
	v_add_f32_e32 v176, v176, v84
	v_add_f32_e32 v177, v177, v85
	v_add_f32_e32 v178, v178, v86
	v_add_f32_e32 v179, v179, v87
	v_add_f32_e32 v176, v176, v88
	v_add_f32_e32 v177, v177, v89
	v_add_f32_e32 v178, v178, v90
	v_add_f32_e32 v179, v179, v91
	v_add_f32_e32 v176, v176, v96
	v_add_f32_e32 v177, v177, v97
	v_add_f32_e32 v178, v178, v98
	v_add_f32_e32 v179, v179, v99
	v_cvt_pk_bf16_f32 v80, v76, v76
	ds_write_b16 v188, v80 offset:0
	v_cvt_pk_bf16_f32 v81, v77, v77
	ds_write_b16 v188, v81 offset:160
	v_cvt_pk_bf16_f32 v124, v78, v78
	ds_write_b16 v188, v124 offset:320
	v_cvt_pk_bf16_f32 v126, v79, v79
	ds_write_b16 v188, v126 offset:480
	v_cvt_pk_bf16_f32 v80, v84, v84
	ds_write_b16 v188, v80 offset:32
	v_cvt_pk_bf16_f32 v81, v85, v85
	ds_write_b16 v188, v81 offset:192
	v_cvt_pk_bf16_f32 v124, v86, v86
	ds_write_b16 v188, v124 offset:352
	v_cvt_pk_bf16_f32 v126, v87, v87
	ds_write_b16 v188, v126 offset:512
	v_cvt_pk_bf16_f32 v80, v88, v88
	ds_write_b16 v188, v80 offset:64
	v_cvt_pk_bf16_f32 v81, v89, v89
	ds_write_b16 v188, v81 offset:224
	v_cvt_pk_bf16_f32 v124, v90, v90
	ds_write_b16 v188, v124 offset:384
	v_cvt_pk_bf16_f32 v126, v91, v91
	ds_write_b16 v188, v126 offset:544
	v_cvt_pk_bf16_f32 v80, v96, v96
	ds_write_b16 v188, v80 offset:96
	v_cvt_pk_bf16_f32 v81, v97, v97
	ds_write_b16 v188, v81 offset:256
	v_cvt_pk_bf16_f32 v124, v98, v98
	ds_write_b16 v188, v124 offset:416
	v_cvt_pk_bf16_f32 v126, v99, v99
	ds_write_b16 v188, v126 offset:576
	v_mul_f32_e32 v100, v100, v180
	v_mul_f32_e32 v101, v101, v181
	v_mul_f32_e32 v102, v102, v182
	v_mul_f32_e32 v103, v103, v183
	v_mul_f32_e32 v132, v132, v180
	v_mul_f32_e32 v133, v133, v181
	v_mul_f32_e32 v134, v134, v182
	v_mul_f32_e32 v135, v135, v183
	v_mul_f32_e32 v140, v140, v180
	v_mul_f32_e32 v141, v141, v181
	v_mul_f32_e32 v142, v142, v182
	v_mul_f32_e32 v143, v143, v183
	v_mul_f32_e32 v144, v144, v180
	v_mul_f32_e32 v145, v145, v181
	v_mul_f32_e32 v146, v146, v182
	v_mul_f32_e32 v147, v147, v183
	s_waitcnt lgkmcnt(0)
	ds_read_b128 v[164:167], v191 offset:0
	ds_read_b128 v[168:171], v191 offset:64
	s_waitcnt lgkmcnt(0)
	v_mfma_f32_16x16x32_bf16 v[100:103], v[164:167], v[44:47], v[100:103]
	v_mfma_f32_16x16x32_bf16 v[132:135], v[164:167], v[48:51], v[132:135]
	v_mfma_f32_16x16x32_bf16 v[140:143], v[164:167], v[52:55], v[140:143]
	v_mfma_f32_16x16x32_bf16 v[144:147], v[164:167], v[56:59], v[144:147]
	v_mfma_f32_16x16x32_bf16 v[100:103], v[168:171], v[60:63], v[100:103]
	v_mfma_f32_16x16x32_bf16 v[132:135], v[168:171], v[64:67], v[132:135]
	v_mfma_f32_16x16x32_bf16 v[140:143], v[168:171], v[68:71], v[140:143]
	v_mfma_f32_16x16x32_bf16 v[144:147], v[168:171], v[72:75], v[144:147]
	s_nop 3
	s_nop 7
	v_add_f32_dpp v176, v176, v176 quad_perm:[1,0,3,2] row_mask:0xf bank_mask:0xf bound_ctrl:1
	v_add_f32_dpp v177, v177, v177 quad_perm:[1,0,3,2] row_mask:0xf bank_mask:0xf bound_ctrl:1
	v_add_f32_dpp v178, v178, v178 quad_perm:[1,0,3,2] row_mask:0xf bank_mask:0xf bound_ctrl:1
	v_add_f32_dpp v179, v179, v179 quad_perm:[1,0,3,2] row_mask:0xf bank_mask:0xf bound_ctrl:1
	v_add_f32_dpp v176, v176, v176 quad_perm:[2,3,0,1] row_mask:0xf bank_mask:0xf bound_ctrl:1
	v_add_f32_dpp v177, v177, v177 quad_perm:[2,3,0,1] row_mask:0xf bank_mask:0xf bound_ctrl:1
	v_add_f32_dpp v178, v178, v178 quad_perm:[2,3,0,1] row_mask:0xf bank_mask:0xf bound_ctrl:1
	v_add_f32_dpp v179, v179, v179 quad_perm:[2,3,0,1] row_mask:0xf bank_mask:0xf bound_ctrl:1
	v_add_f32_dpp v176, v176, v176 row_half_mirror row_mask:0xf bank_mask:0xf bound_ctrl:1
	v_add_f32_dpp v177, v177, v177 row_half_mirror row_mask:0xf bank_mask:0xf bound_ctrl:1
	v_add_f32_dpp v178, v178, v178 row_half_mirror row_mask:0xf bank_mask:0xf bound_ctrl:1
	v_add_f32_dpp v179, v179, v179 row_half_mirror row_mask:0xf bank_mask:0xf bound_ctrl:1
	v_add_f32_dpp v176, v176, v176 row_ror:8 row_mask:0xf bank_mask:0xf bound_ctrl:1
	v_add_f32_dpp v177, v177, v177 row_ror:8 row_mask:0xf bank_mask:0xf bound_ctrl:1
	v_add_f32_dpp v178, v178, v178 row_ror:8 row_mask:0xf bank_mask:0xf bound_ctrl:1
	v_add_f32_dpp v179, v179, v179 row_ror:8 row_mask:0xf bank_mask:0xf bound_ctrl:1
	v_rcp_f32_e32 v180, v176
	v_rcp_f32_e32 v181, v177
	v_rcp_f32_e32 v182, v178
	v_rcp_f32_e32 v183, v179
	s_nop 0
	v_fma_f32 v184, -v176, v180, 1.0
	v_fma_f32 v180, v184, v180, v180
	v_fma_f32 v185, -v177, v181, 1.0
	v_fma_f32 v181, v185, v181, v181
	v_fma_f32 v186, -v178, v182, 1.0
	v_fma_f32 v182, v186, v182, v182
	v_fma_f32 v187, -v179, v183, 1.0
	v_fma_f32 v183, v187, v183, v183
	v_add_u32_e32 v80, 0x0, v208
	v_add_u32_e32 v81, 0x1000, v208
	v_add_u32_e32 v124, 0x2000, v208
	v_add_u32_e32 v126, 0x3000, v208
	v_mul_f32_e32 v100, v100, v180
	v_cvt_pk_bf16_f32 v100, v100, v100
	global_store_short v80, v100, s[20:21] offset:0
	v_mul_f32_e32 v101, v101, v181
	v_cvt_pk_bf16_f32 v101, v101, v101
	global_store_short v81, v101, s[20:21] offset:0
	v_mul_f32_e32 v102, v102, v182
	v_cvt_pk_bf16_f32 v102, v102, v102
	global_store_short v124, v102, s[20:21] offset:0
	v_mul_f32_e32 v103, v103, v183
	v_cvt_pk_bf16_f32 v103, v103, v103
	global_store_short v126, v103, s[20:21] offset:0
	v_mul_f32_e32 v132, v132, v180
	v_cvt_pk_bf16_f32 v132, v132, v132
	global_store_short v80, v132, s[20:21] offset:32
	v_mul_f32_e32 v133, v133, v181
	v_cvt_pk_bf16_f32 v133, v133, v133
	global_store_short v81, v133, s[20:21] offset:32
	v_mul_f32_e32 v134, v134, v182
	v_cvt_pk_bf16_f32 v134, v134, v134
	global_store_short v124, v134, s[20:21] offset:32
	v_mul_f32_e32 v135, v135, v183
	v_cvt_pk_bf16_f32 v135, v135, v135
	global_store_short v126, v135, s[20:21] offset:32
	v_mul_f32_e32 v140, v140, v180
	v_cvt_pk_bf16_f32 v140, v140, v140
	global_store_short v80, v140, s[20:21] offset:64
	v_mul_f32_e32 v141, v141, v181
	v_cvt_pk_bf16_f32 v141, v141, v141
	global_store_short v81, v141, s[20:21] offset:64
	v_mul_f32_e32 v142, v142, v182
	v_cvt_pk_bf16_f32 v142, v142, v142
	global_store_short v124, v142, s[20:21] offset:64
	v_mul_f32_e32 v143, v143, v183
	v_cvt_pk_bf16_f32 v143, v143, v143
	global_store_short v126, v143, s[20:21] offset:64
	v_mul_f32_e32 v144, v144, v180
	v_cvt_pk_bf16_f32 v144, v144, v144
	global_store_short v80, v144, s[20:21] offset:96
	v_mul_f32_e32 v145, v145, v181
	v_cvt_pk_bf16_f32 v145, v145, v145
	global_store_short v81, v145, s[20:21] offset:96
	v_mul_f32_e32 v146, v146, v182
	v_cvt_pk_bf16_f32 v146, v146, v146
	global_store_short v124, v146, s[20:21] offset:96
	v_mul_f32_e32 v147, v147, v183
	v_cvt_pk_bf16_f32 v147, v147, v147
	global_store_short v126, v147, s[20:21] offset:96
	s_add_i32 s89, s89, 1
	s_addk_i32 s88, 0x800
	s_cmp_eq_u32 s89, 16
	s_cbranch_scc1 .LBB0_719
	s_branch .LBB0_459
